# v22 with every per-segment s_setprio flip in the GEMM K-loops deleted and one static s_setprio 1 for waves 4-7 at kernel entry
# speedup vs baseline: 1.0050x; 1.0022x over previous
; template <class T> __device__ __forceinline__ T* as_global(T* p) { return (T*)(__attribute__((address_space(1))) T*)p; }
; __global__ void __launch_bounds__(NTHREADS, 2) fwd_kernel(Params prm) {
;     extern __shared__ __attribute__((aligned(16))) unsigned char lds[];
;     __shared__ int s_unit;
;     __shared__ unsigned s_bar[2];
;     cg::grid_group grid = cg::this_grid();
;     if (threadIdx.x < 2) s_bar[threadIdx.x] = 0u;
;     __syncthreads();
;     if (blockIdx.x == 0) { unsigned* ctl0 = (unsigned*)(as_global(prm.ws) + WS_CTL); for (int i = threadIdx.x; i < 8192; i += NTHREADS) ctl0[i] = 0u; }
_Z10fwd_kernel6Params:
	s_load_dwordx16 s[52:67], s[0:1], 0xc0
	s_load_dword s20, s[0:1], 0x108
	s_load_dwordx2 s[82:83], s[0:1], 0x100
	s_mov_b32 s80, s2
	s_add_u32 s2, s0, 0x100
	s_addc_u32 s3, s1, 0
	v_and_b32_e32 v194, 0x3ff, v0
	v_writelane_b32 v254, s2, 0
	v_cmp_gt_u32_e32 vcc, 2, v194
	s_nop 0
	v_writelane_b32 v254, s3, 1
	s_and_saveexec_b64 s[2:3], vcc
	v_lshlrev_b32_e32 v1, 2, v194
	v_mov_b32_e32 v2, 0
	ds_write_b32 v1, v2
	s_or_b64 exec, exec, s[2:3]
	v_readfirstlane_b32 s32, v194
	s_nop 3
	s_lshr_b32 s32, s32, 6
	s_cmp_ge_u32 s32, 4
	s_cbranch_scc0 .Lprio_done
	s_setprio 1
.Lprio_done:
	s_load_dwordx16 s[36:51], s[0:1], 0x0
	s_load_dwordx16 s[4:19], s[0:1], 0x40
	s_cmp_lg_u32 s80, 0
	s_mov_b32 s87, 0
	s_waitcnt lgkmcnt(0)
	s_barrier
	v_writelane_b32 v254, s4, 2
	s_nop 1
	v_writelane_b32 v254, s5, 3
	v_writelane_b32 v254, s6, 4
	v_writelane_b32 v254, s7, 5
	v_writelane_b32 v254, s8, 6
	v_writelane_b32 v254, s9, 7
	v_writelane_b32 v254, s10, 8
	v_writelane_b32 v254, s11, 9
	v_writelane_b32 v254, s12, 10
	v_writelane_b32 v254, s13, 11
	v_writelane_b32 v254, s14, 12
	v_writelane_b32 v254, s15, 13
	v_writelane_b32 v254, s16, 14
	v_writelane_b32 v254, s17, 15
	v_writelane_b32 v254, s18, 16
	v_writelane_b32 v254, s19, 17
	s_load_dwordx16 s[4:19], s[0:1], 0x80
	s_waitcnt lgkmcnt(0)
	v_writelane_b32 v254, s4, 18
	s_nop 1
	v_writelane_b32 v254, s5, 19
	v_writelane_b32 v254, s6, 20
	v_writelane_b32 v254, s7, 21
	v_writelane_b32 v254, s8, 22
	v_writelane_b32 v254, s9, 23
	v_writelane_b32 v254, s10, 24
	v_writelane_b32 v254, s11, 25
	v_writelane_b32 v254, s12, 26
	v_writelane_b32 v254, s13, 27
	v_writelane_b32 v254, s14, 28
	v_writelane_b32 v254, s15, 29
	v_writelane_b32 v254, s16, 30
	v_writelane_b32 v254, s17, 31
	v_writelane_b32 v254, s18, 32
	v_writelane_b32 v254, s19, 33
	s_nop 0
	v_readlane_b32 s4, v254, 2
	v_readlane_b32 s5, v254, 3
	v_readlane_b32 s6, v254, 4
	v_readlane_b32 s7, v254, 5
	v_readlane_b32 s8, v254, 6
	v_readlane_b32 s9, v254, 7
	v_readlane_b32 s10, v254, 8
	v_readlane_b32 s11, v254, 9
	v_readlane_b32 s12, v254, 10
	v_readlane_b32 s13, v254, 11
	v_readlane_b32 s14, v254, 12
	v_readlane_b32 s15, v254, 13
	v_readlane_b32 s16, v254, 14
	v_readlane_b32 s17, v254, 15
	v_readlane_b32 s18, v254, 16
	v_readlane_b32 s19, v254, 17
	v_writelane_b32 v254, s36, 34
	s_nop 1
	v_writelane_b32 v254, s37, 35
	v_writelane_b32 v254, s38, 36
	v_writelane_b32 v254, s39, 37
	v_writelane_b32 v254, s40, 38
	v_writelane_b32 v254, s41, 39
	v_writelane_b32 v254, s42, 40
	v_writelane_b32 v254, s43, 41
	v_writelane_b32 v254, s44, 42
	v_writelane_b32 v254, s45, 43
	v_writelane_b32 v254, s46, 44
	v_writelane_b32 v254, s47, 45
	v_writelane_b32 v254, s48, 46
	v_writelane_b32 v254, s49, 47
	v_writelane_b32 v254, s50, 48
	v_writelane_b32 v254, s51, 49
	s_cbranch_scc1 .LBB0_9
	v_lshrrev_b32_e32 v1, 9, v194
	v_sub_u32_e32 v6, 16, v1
	v_and_b32_e32 v1, 30, v6
	v_add_u32_e32 v195, 0x200, v194
	s_mov_b64 s[0:1], 0
	v_mov_b32_e32 v3, 0
	v_mov_b32_e32 v7, v1
	v_mov_b64_e32 v[4:5], v[194:195]

; #define PG8_STAGE(bufoff, gbase, voff) do { _Pragma("unroll") for (int _i = 0; _i < 2; ++_i) \
;         __builtin_amdgcn_global_load_lds((const unsigned*)((const char*)(gbase) + (voff)[_i]), (LAS unsigned*)(lds + (bufoff) + ldsw + _i * 8192), 16, 0, 0); } while (0)
; #define PG8_LDA(dst, b, h) do { _Pragma("unroll") for (int m = 0; m < 4; ++m) _Pragma("unroll") for (int k = 0; k < 2; ++k) dst[m][k] = *(const LAS bf16x8*)(lds + PG8_SA(b, h) + aoff + m * 2048 + k * 1024); } while (0)
; #define PG8_LDB(dst, b, h) do { _Pragma("unroll") for (int n = 0; n < 2; ++n) _Pragma("unroll") for (int k = 0; k < 2; ++k) dst[n][k] = *(const LAS bf16x8*)(lds + PG8_SB(b, h) + boff + n * 2048 + k * 1024); } while (0)
; #define PG8_MMA(ai, bj, At, Bt) do { __builtin_amdgcn_s_setprio(1); _Pragma("unroll") for (int m = 0; m < 4; ++m) _Pragma("unroll") for (int n = 0; n < 2; ++n) _Pragma("unroll") for (int k = 0; k < 2; ++k) \
;         acc[ai][bj][m][n] = __builtin_amdgcn_mfma_f32_16x16x32_bf16(Bt[n][k], At[m][k], acc[ai][bj][m][n], 0, 0, 0); __builtin_amdgcn_s_setprio(0); } while (0)
; #define PG8_WAIT_V(n) asm volatile("s_waitcnt vmcnt(" #n ")" ::: "memory")
; #define PG8_WAIT_L(n) asm volatile("s_waitcnt lgkmcnt(" #n ")" ::: "memory")
; #define PG8_BAR __builtin_amdgcn_s_barrier()
; #define PG8_SCHED __builtin_amdgcn_sched_barrier(0)
; template <class Epi, class Sched>
; __device__ __forceinline__ void gemm_phase(const int tid, LAS unsigned char* lds, const Gemm g, const Sched& S, const Epi& E) {
;     ...
;             PG8_LDB(B0, 0, 0); PG8_LDB(B1, 0, 1); PG8_SCHED; PG8_LDA(At, 0, 0); PG8_STAGE(PG8_SA(1, 1), a1 + hstepA, voffA);
;             PG8_WAIT_V(8); PG8_WAIT_L(0); PG8_BAR; PG8_MMA(0, 0, At, B0); PG8_MMA(0, 1, At, B1); PG8_BAR; PG8_SCHED;
;             PG8_LDA(At, 0, 1); PG8_STAGE(PG8_SB(0, 0), b2, voffB); PG8_STAGE(PG8_SB(0, 1), b2 + hstepB, voffB); PG8_STAGE(PG8_SA(0, 0), a2, voffA);
;             PG8_WAIT_V(8); PG8_WAIT_L(0); PG8_BAR; PG8_MMA(1, 0, At, B0); PG8_MMA(1, 1, At, B1); PG8_BAR; PG8_SCHED;
.LBB0_135:
	s_add_u32 s24, s6, 0x4000
	s_addc_u32 s25, s7, 0
	s_cmp_eq_u32 s66, 28
	s_cselect_b32 s28, s19, s24
	s_cselect_b32 s29, s13, s25
	s_cselect_b32 s26, s63, s64
	s_cselect_b32 s27, s17, s65
	s_add_u32 s24, s28, 0x8000
	s_addc_u32 s25, s29, 0
	s_add_i32 s67, 16, 0x10000
	s_add_i32 s78, 16, 0x14000
	v_add_u32_e32 v78, s67, v180
	v_add_u32_e32 v178, s78, v180
	ds_read_b128 v[58:61], v78
	ds_read_b128 v[62:65], v78 offset:1024
	ds_read_b128 v[74:77], v78 offset:2048
	ds_read_b128 v[78:81], v78 offset:3072
	ds_read_b128 v[174:177], v178
	ds_read_b128 v[182:185], v178 offset:1024
	ds_read_b128 v[186:189], v178 offset:2048
	ds_read_b128 v[190:193], v178 offset:3072
	s_add_i32 m0, s15, 0xc000
	ds_read_b128 v[208:211], v181
	ds_read_b128 v[212:215], v181 offset:1024
	ds_read_b128 v[216:219], v181 offset:2048
	ds_read_b128 v[220:223], v181 offset:3072
	ds_read_b128 v[236:239], v181 offset:4096
	ds_read_b128 v[244:247], v181 offset:5120
	ds_read_b128 v[248:251], v181 offset:6144
	ds_read_b128 v[204:207], v181 offset:7168
	global_load_lds_dwordx4 v172, s[6:7]
	s_add_i32 m0, s15, 0xe000
	s_nop 0
	global_load_lds_dwordx4 v170, s[6:7]
	s_waitcnt vmcnt(8)
	s_waitcnt lgkmcnt(0)
	s_barrier
	s_waitcnt lgkmcnt(0)
	v_mfma_f32_16x16x32_bf16 v[142:145], v[58:61], v[208:211], v[142:145]
	v_mfma_f32_16x16x32_bf16 v[138:141], v[74:77], v[208:211], v[138:141]
	v_mfma_f32_16x16x32_bf16 v[126:129], v[58:61], v[216:219], v[126:129]
	v_mfma_f32_16x16x32_bf16 v[122:125], v[74:77], v[216:219], v[122:125]
	v_mfma_f32_16x16x32_bf16 v[110:113], v[58:61], v[236:239], v[110:113]
	v_mfma_f32_16x16x32_bf16 v[106:109], v[74:77], v[236:239], v[106:109]
	v_mfma_f32_16x16x32_bf16 v[94:97], v[58:61], v[248:251], v[94:97]
	v_mfma_f32_16x16x32_bf16 v[90:93], v[74:77], v[248:251], v[90:93]
	v_mfma_f32_16x16x32_bf16 v[142:145], v[62:65], v[212:215], v[142:145]
	v_mfma_f32_16x16x32_bf16 v[138:141], v[78:81], v[212:215], v[138:141]
	v_mfma_f32_16x16x32_bf16 v[126:129], v[62:65], v[220:223], v[126:129]
	v_mfma_f32_16x16x32_bf16 v[122:125], v[78:81], v[220:223], v[122:125]
	v_mfma_f32_16x16x32_bf16 v[110:113], v[62:65], v[244:247], v[110:113]
	v_mfma_f32_16x16x32_bf16 v[106:109], v[78:81], v[244:247], v[106:109]
	v_mfma_f32_16x16x32_bf16 v[94:97], v[62:65], v[204:207], v[94:97]
	v_mfma_f32_16x16x32_bf16 v[90:93], v[78:81], v[204:207], v[90:93]
	v_mfma_f32_16x16x32_bf16 v[134:137], v[174:177], v[208:211], v[134:137]
	v_mfma_f32_16x16x32_bf16 v[130:133], v[186:189], v[208:211], v[130:133]
	v_mfma_f32_16x16x32_bf16 v[118:121], v[174:177], v[216:219], v[118:121]
	v_mfma_f32_16x16x32_bf16 v[114:117], v[186:189], v[216:219], v[114:117]
	v_mfma_f32_16x16x32_bf16 v[102:105], v[174:177], v[236:239], v[102:105]
	v_mfma_f32_16x16x32_bf16 v[98:101], v[186:189], v[236:239], v[98:101]
	v_mfma_f32_16x16x32_bf16 v[86:89], v[174:177], v[248:251], v[86:89]
	v_mfma_f32_16x16x32_bf16 v[82:85], v[186:189], v[248:251], v[82:85]
	v_mfma_f32_16x16x32_bf16 v[134:137], v[182:185], v[212:215], v[134:137]
	v_mfma_f32_16x16x32_bf16 v[130:133], v[190:193], v[212:215], v[130:133]
	v_mfma_f32_16x16x32_bf16 v[118:121], v[182:185], v[220:223], v[118:121]
	v_mfma_f32_16x16x32_bf16 v[114:117], v[190:193], v[220:223], v[114:117]
	v_mfma_f32_16x16x32_bf16 v[102:105], v[182:185], v[244:247], v[102:105]
	v_mfma_f32_16x16x32_bf16 v[98:101], v[190:193], v[244:247], v[98:101]
	v_mfma_f32_16x16x32_bf16 v[86:89], v[182:185], v[204:207], v[86:89]
	v_mfma_f32_16x16x32_bf16 v[82:85], v[190:193], v[204:207], v[82:85]
	s_barrier
	s_add_i32 s67, s67, s54
	s_mov_b32 m0, s67
	ds_read_b128 v[204:207], v181 offset:16384
	ds_read_b128 v[208:211], v181 offset:17408
	ds_read_b128 v[212:215], v181 offset:18432
	ds_read_b128 v[216:219], v181 offset:19456
	ds_read_b128 v[220:223], v181 offset:20480
	ds_read_b128 v[236:239], v181 offset:21504
	ds_read_b128 v[244:247], v181 offset:22528
	ds_read_b128 v[248:251], v181 offset:23552
	global_load_lds_dwordx4 v0, s[26:27]
	s_add_i32 m0, s67, 0x2000
	s_add_u32 s76, s26, 0x4000
	s_addc_u32 s77, s27, 0
	s_add_i32 s67, s78, s54
	global_load_lds_dwordx4 v150, s[26:27]
	s_mov_b32 m0, s67
	s_nop 0
	global_load_lds_dwordx4 v0, s[76:77]
	s_add_i32 m0, s67, 0x2000
	s_nop 0
	global_load_lds_dwordx4 v150, s[76:77]
	s_mov_b32 m0, s15
	s_nop 0
	global_load_lds_dwordx4 v146, s[28:29]
	v_lshl_add_u64 v[178:179], s[28:29], 0, v[148:149]
	s_mov_b32 m0, s55
	s_nop 0
	global_load_lds_dwordx4 v[178:179], off
	s_waitcnt vmcnt(8)
	s_waitcnt lgkmcnt(0)
	s_barrier
	s_waitcnt lgkmcnt(0)
	v_mfma_f32_16x16x32_bf16 v[70:73], v[58:61], v[204:207], v[70:73]
	v_mfma_f32_16x16x32_bf16 v[66:69], v[74:77], v[204:207], v[66:69]
	v_mfma_f32_16x16x32_bf16 v[46:49], v[58:61], v[212:215], v[46:49]
	v_mfma_f32_16x16x32_bf16 v[42:45], v[74:77], v[212:215], v[42:45]
	v_mfma_f32_16x16x32_bf16 v[30:33], v[58:61], v[220:223], v[30:33]
	v_mfma_f32_16x16x32_bf16 v[26:29], v[74:77], v[220:223], v[26:29]
	v_mfma_f32_16x16x32_bf16 v[14:17], v[58:61], v[244:247], v[14:17]
	v_mfma_f32_16x16x32_bf16 v[10:13], v[74:77], v[244:247], v[10:13]
	v_mfma_f32_16x16x32_bf16 v[70:73], v[62:65], v[208:211], v[70:73]
	v_mfma_f32_16x16x32_bf16 v[66:69], v[78:81], v[208:211], v[66:69]
	v_mfma_f32_16x16x32_bf16 v[46:49], v[62:65], v[216:219], v[46:49]
	v_mfma_f32_16x16x32_bf16 v[42:45], v[78:81], v[216:219], v[42:45]
	v_mfma_f32_16x16x32_bf16 v[30:33], v[62:65], v[236:239], v[30:33]
	v_mfma_f32_16x16x32_bf16 v[26:29], v[78:81], v[236:239], v[26:29]
	v_mfma_f32_16x16x32_bf16 v[14:17], v[62:65], v[248:251], v[14:17]
	v_mfma_f32_16x16x32_bf16 v[10:13], v[78:81], v[248:251], v[10:13]
	v_mfma_f32_16x16x32_bf16 v[54:57], v[174:177], v[204:207], v[54:57]
	v_mfma_f32_16x16x32_bf16 v[50:53], v[186:189], v[204:207], v[50:53]
	v_mfma_f32_16x16x32_bf16 v[38:41], v[174:177], v[212:215], v[38:41]
	v_mfma_f32_16x16x32_bf16 v[34:37], v[186:189], v[212:215], v[34:37]
	v_mfma_f32_16x16x32_bf16 v[22:25], v[174:177], v[220:223], v[22:25]
	v_mfma_f32_16x16x32_bf16 v[18:21], v[186:189], v[220:223], v[18:21]
	v_mfma_f32_16x16x32_bf16 v[6:9], v[174:177], v[244:247], v[6:9]
	v_mfma_f32_16x16x32_bf16 v[2:5], v[186:189], v[244:247], v[2:5]
	v_mfma_f32_16x16x32_bf16 v[54:57], v[182:185], v[208:211], v[54:57]
	v_mfma_f32_16x16x32_bf16 v[50:53], v[190:193], v[208:211], v[50:53]
	v_mfma_f32_16x16x32_bf16 v[38:41], v[182:185], v[216:219], v[38:41]
	v_mfma_f32_16x16x32_bf16 v[34:37], v[190:193], v[216:219], v[34:37]
	v_mfma_f32_16x16x32_bf16 v[22:25], v[182:185], v[236:239], v[22:25]
	v_mfma_f32_16x16x32_bf16 v[18:21], v[190:193], v[236:239], v[18:21]
	v_mfma_f32_16x16x32_bf16 v[6:9], v[182:185], v[248:251], v[6:9]
	v_mfma_f32_16x16x32_bf16 v[2:5], v[190:193], v[248:251], v[2:5]
	s_barrier
; #define PG8_STAGE(bufoff, gbase, voff) do { _Pragma("unroll") for (int _i = 0; _i < 2; ++_i) \
;         __builtin_amdgcn_global_load_lds((const unsigned*)((const char*)(gbase) + (voff)[_i]), (LAS unsigned*)(lds + (bufoff) + ldsw + _i * 8192), 16, 0, 0); } while (0)
; #define PG8_LDA(dst, b, h) do { _Pragma("unroll") for (int m = 0; m < 4; ++m) _Pragma("unroll") for (int k = 0; k < 2; ++k) dst[m][k] = *(const LAS bf16x8*)(lds + PG8_SA(b, h) + aoff + m * 2048 + k * 1024); } while (0)
; #define PG8_LDB(dst, b, h) do { _Pragma("unroll") for (int n = 0; n < 2; ++n) _Pragma("unroll") for (int k = 0; k < 2; ++k) dst[n][k] = *(const LAS bf16x8*)(lds + PG8_SB(b, h) + boff + n * 2048 + k * 1024); } while (0)
; #define PG8_WAIT_V(n) asm volatile("s_waitcnt vmcnt(" #n ")" ::: "memory")
; template <class Epi, class Sched>
; __device__ __forceinline__ void gemm_phase(const int tid, LAS unsigned char* lds, const Gemm g, const Sched& S, const Epi& E) {
;     ...
;         for (int t = 0; t < nt; t += 2) {
;             const bool last = (t == nt - 2);
;             const char* a1 = cA + (size_t)(t + 1) * kstepA;
;             const char* a2 = last ? nA : cA + (size_t)(t + 2) * kstepA; const char* b2 = last ? nB : cB + (size_t)(t + 2) * kstepB;
;             const char* a3 = a2 + kstepA; const char* b3 = b2 + kstepB;
;             PG8_LDB(B0, 0, 0); PG8_LDB(B1, 0, 1); PG8_SCHED; PG8_LDA(At, 0, 0); PG8_STAGE(PG8_SA(1, 1), a1 + hstepA, voffA);
;             PG8_WAIT_V(8); PG8_WAIT_L(0); PG8_BAR; PG8_MMA(0, 0, At, B0); PG8_MMA(0, 1, At, B1); PG8_BAR; PG8_SCHED;
;             PG8_LDA(At, 0, 1); PG8_STAGE(PG8_SB(0, 0), b2, voffB); PG8_STAGE(PG8_SB(0, 1), b2 + hstepB, voffB); PG8_STAGE(PG8_SA(0, 0), a2, voffA);
;             PG8_WAIT_V(8); PG8_WAIT_L(0); PG8_BAR; PG8_MMA(1, 0, At, B0); PG8_MMA(1, 1, At, B1); PG8_BAR; PG8_SCHED;
;             PG8_LDB(B0, 1, 0); PG8_LDB(B1, 1, 1); PG8_SCHED; PG8_LDA(At, 1, 0); PG8_STAGE(PG8_SA(0, 1), a2 + hstepA, voffA);
;             PG8_WAIT_V(8); PG8_WAIT_L(0); PG8_BAR; PG8_MMA(0, 0, At, B0); PG8_MMA(0, 1, At, B1); PG8_BAR; PG8_SCHED;
;             PG8_LDA(At, 1, 1); PG8_STAGE(PG8_SB(1, 0), b3, voffB); PG8_STAGE(PG8_SB(1, 1), b3 + hstepB, voffB); PG8_STAGE(PG8_SA(1, 0), a3, voffA);
;             PG8_WAIT_V(8); PG8_WAIT_L(0); PG8_BAR; PG8_MMA(1, 0, At, B0); PG8_MMA(1, 1, At, B1); PG8_BAR; PG8_SCHED;
;         }
;         if (wr == 0) PG8_BAR;
	s_add_i32 s67, 16, 0x18000
	s_add_i32 s76, 16, 0x1c000
	v_add_u32_e32 v78, s67, v180
	v_add_u32_e32 v178, s76, v180
	ds_read_b128 v[58:61], v78
	ds_read_b128 v[62:65], v78 offset:1024
	ds_read_b128 v[74:77], v78 offset:2048
	ds_read_b128 v[78:81], v78 offset:3072
	ds_read_b128 v[174:177], v178
	ds_read_b128 v[182:185], v178 offset:1024
	ds_read_b128 v[186:189], v178 offset:2048
	ds_read_b128 v[190:193], v178 offset:3072
	s_add_u32 s28, s28, 0x4000
	s_addc_u32 s29, s29, 0
	s_mov_b32 m0, s56
	ds_read_b128 v[204:207], v181 offset:32768
	ds_read_b128 v[208:211], v181 offset:33792
	ds_read_b128 v[212:215], v181 offset:34816
	ds_read_b128 v[216:219], v181 offset:35840
	ds_read_b128 v[220:223], v181 offset:36864
	ds_read_b128 v[236:239], v181 offset:37888
	ds_read_b128 v[244:247], v181 offset:38912
	ds_read_b128 v[248:251], v181 offset:39936
	global_load_lds_dwordx4 v146, s[28:29]
	s_mov_b32 m0, s57
	s_nop 0
	global_load_lds_dwordx4 v148, s[28:29]
	s_waitcnt vmcnt(8)
	s_waitcnt lgkmcnt(0)
	s_barrier
	s_waitcnt lgkmcnt(0)
	v_mfma_f32_16x16x32_bf16 v[142:145], v[58:61], v[204:207], v[142:145]
	v_mfma_f32_16x16x32_bf16 v[138:141], v[74:77], v[204:207], v[138:141]
	v_mfma_f32_16x16x32_bf16 v[126:129], v[58:61], v[212:215], v[126:129]
	v_mfma_f32_16x16x32_bf16 v[122:125], v[74:77], v[212:215], v[122:125]
	v_mfma_f32_16x16x32_bf16 v[110:113], v[58:61], v[220:223], v[110:113]
	v_mfma_f32_16x16x32_bf16 v[106:109], v[74:77], v[220:223], v[106:109]
	v_mfma_f32_16x16x32_bf16 v[94:97], v[58:61], v[244:247], v[94:97]
	v_mfma_f32_16x16x32_bf16 v[90:93], v[74:77], v[244:247], v[90:93]
	v_mfma_f32_16x16x32_bf16 v[142:145], v[62:65], v[208:211], v[142:145]
	v_mfma_f32_16x16x32_bf16 v[138:141], v[78:81], v[208:211], v[138:141]
	v_mfma_f32_16x16x32_bf16 v[126:129], v[62:65], v[216:219], v[126:129]
	v_mfma_f32_16x16x32_bf16 v[122:125], v[78:81], v[216:219], v[122:125]
	v_mfma_f32_16x16x32_bf16 v[110:113], v[62:65], v[236:239], v[110:113]
	v_mfma_f32_16x16x32_bf16 v[106:109], v[78:81], v[236:239], v[106:109]
	v_mfma_f32_16x16x32_bf16 v[94:97], v[62:65], v[248:251], v[94:97]
	v_mfma_f32_16x16x32_bf16 v[90:93], v[78:81], v[248:251], v[90:93]
	v_mfma_f32_16x16x32_bf16 v[134:137], v[174:177], v[204:207], v[134:137]
	v_mfma_f32_16x16x32_bf16 v[130:133], v[186:189], v[204:207], v[130:133]
	v_mfma_f32_16x16x32_bf16 v[118:121], v[174:177], v[212:215], v[118:121]
	v_mfma_f32_16x16x32_bf16 v[114:117], v[186:189], v[212:215], v[114:117]
	v_mfma_f32_16x16x32_bf16 v[102:105], v[174:177], v[220:223], v[102:105]
	v_mfma_f32_16x16x32_bf16 v[98:101], v[186:189], v[220:223], v[98:101]
	v_mfma_f32_16x16x32_bf16 v[86:89], v[174:177], v[244:247], v[86:89]
	v_mfma_f32_16x16x32_bf16 v[82:85], v[186:189], v[244:247], v[82:85]
	v_mfma_f32_16x16x32_bf16 v[134:137], v[182:185], v[208:211], v[134:137]
	v_mfma_f32_16x16x32_bf16 v[130:133], v[190:193], v[208:211], v[130:133]
	v_mfma_f32_16x16x32_bf16 v[118:121], v[182:185], v[216:219], v[118:121]
	v_mfma_f32_16x16x32_bf16 v[114:117], v[190:193], v[216:219], v[114:117]
	v_mfma_f32_16x16x32_bf16 v[102:105], v[182:185], v[236:239], v[102:105]
	v_mfma_f32_16x16x32_bf16 v[98:101], v[190:193], v[236:239], v[98:101]
	v_mfma_f32_16x16x32_bf16 v[86:89], v[182:185], v[248:251], v[86:89]
	v_mfma_f32_16x16x32_bf16 v[82:85], v[190:193], v[248:251], v[82:85]
	s_barrier
	s_add_u32 s28, s26, 0x8000
	s_addc_u32 s29, s27, 0
	s_add_i32 s67, s67, s54
	s_mov_b32 m0, s67
	ds_read_b128 v[204:207], v181 offset:49152
	ds_read_b128 v[208:211], v181 offset:50176
	ds_read_b128 v[212:215], v181 offset:51200
	ds_read_b128 v[216:219], v181 offset:52224
	ds_read_b128 v[220:223], v181 offset:53248
	ds_read_b128 v[236:239], v181 offset:54272
	ds_read_b128 v[244:247], v181 offset:55296
	ds_read_b128 v[248:251], v181 offset:56320
	global_load_lds_dwordx4 v0, s[28:29]
	s_add_i32 m0, s67, 0x2000
	s_add_u32 s26, s26, 0xc000
	s_addc_u32 s27, s27, 0
	global_load_lds_dwordx4 v150, s[28:29]
	s_add_i32 s28, s76, s54
	s_mov_b32 m0, s28
	s_nop 0
	global_load_lds_dwordx4 v0, s[26:27]
	s_add_i32 m0, s28, 0x2000
	s_nop 0
	global_load_lds_dwordx4 v150, s[26:27]
	s_mov_b32 m0, s58
	s_nop 0
	global_load_lds_dwordx4 v146, s[24:25]
	v_lshl_add_u64 v[178:179], s[24:25], 0, v[148:149]
	s_mov_b32 m0, s59
	s_nop 0
	global_load_lds_dwordx4 v[178:179], off
	s_waitcnt vmcnt(8)
	s_waitcnt lgkmcnt(0)
	s_barrier
	s_waitcnt lgkmcnt(0)
	v_mfma_f32_16x16x32_bf16 v[70:73], v[58:61], v[204:207], v[70:73]
	v_mfma_f32_16x16x32_bf16 v[66:69], v[74:77], v[204:207], v[66:69]
	v_mfma_f32_16x16x32_bf16 v[46:49], v[58:61], v[212:215], v[46:49]
	v_mfma_f32_16x16x32_bf16 v[42:45], v[74:77], v[212:215], v[42:45]
	v_mfma_f32_16x16x32_bf16 v[30:33], v[58:61], v[220:223], v[30:33]
	v_mfma_f32_16x16x32_bf16 v[26:29], v[74:77], v[220:223], v[26:29]
	v_mfma_f32_16x16x32_bf16 v[14:17], v[58:61], v[244:247], v[14:17]
	v_mfma_f32_16x16x32_bf16 v[10:13], v[74:77], v[244:247], v[10:13]
	v_mfma_f32_16x16x32_bf16 v[70:73], v[62:65], v[208:211], v[70:73]
	v_mfma_f32_16x16x32_bf16 v[66:69], v[78:81], v[208:211], v[66:69]
	v_mfma_f32_16x16x32_bf16 v[46:49], v[62:65], v[216:219], v[46:49]
	v_mfma_f32_16x16x32_bf16 v[42:45], v[78:81], v[216:219], v[42:45]
	v_mfma_f32_16x16x32_bf16 v[30:33], v[62:65], v[236:239], v[30:33]
	v_mfma_f32_16x16x32_bf16 v[26:29], v[78:81], v[236:239], v[26:29]
	v_mfma_f32_16x16x32_bf16 v[14:17], v[62:65], v[248:251], v[14:17]
	v_mfma_f32_16x16x32_bf16 v[10:13], v[78:81], v[248:251], v[10:13]
	v_mfma_f32_16x16x32_bf16 v[54:57], v[174:177], v[204:207], v[54:57]
	v_mfma_f32_16x16x32_bf16 v[50:53], v[186:189], v[204:207], v[50:53]
	v_mfma_f32_16x16x32_bf16 v[38:41], v[174:177], v[212:215], v[38:41]
	v_mfma_f32_16x16x32_bf16 v[34:37], v[186:189], v[212:215], v[34:37]
	v_mfma_f32_16x16x32_bf16 v[22:25], v[174:177], v[220:223], v[22:25]
	v_mfma_f32_16x16x32_bf16 v[18:21], v[186:189], v[220:223], v[18:21]
	v_mfma_f32_16x16x32_bf16 v[6:9], v[174:177], v[244:247], v[6:9]
	v_mfma_f32_16x16x32_bf16 v[2:5], v[186:189], v[244:247], v[2:5]
	v_mfma_f32_16x16x32_bf16 v[54:57], v[182:185], v[208:211], v[54:57]
	v_mfma_f32_16x16x32_bf16 v[50:53], v[190:193], v[208:211], v[50:53]
	v_mfma_f32_16x16x32_bf16 v[38:41], v[182:185], v[216:219], v[38:41]
	v_mfma_f32_16x16x32_bf16 v[34:37], v[190:193], v[216:219], v[34:37]
	v_mfma_f32_16x16x32_bf16 v[22:25], v[182:185], v[236:239], v[22:25]
	v_mfma_f32_16x16x32_bf16 v[18:21], v[190:193], v[236:239], v[18:21]
	v_mfma_f32_16x16x32_bf16 v[6:9], v[182:185], v[248:251], v[6:9]
	v_mfma_f32_16x16x32_bf16 v[2:5], v[190:193], v[248:251], v[2:5]
	s_barrier
	s_add_i32 s66, s66, 2
	s_add_u32 s64, s64, 0x10000
	s_addc_u32 s65, s65, 0
	s_add_u32 s6, s6, 0x10000
	s_addc_u32 s7, s7, 0
	s_cmp_gt_u32 s66, 29
	s_cbranch_scc0 .LBB0_135
	s_and_b64 vcc, exec, s[10:11]
	s_cbranch_vccz .LBB0_138
	s_barrier

; #define PG8_STAGE(bufoff, gbase, voff) do { _Pragma("unroll") for (int _i = 0; _i < 2; ++_i) \
;         __builtin_amdgcn_global_load_lds((const unsigned*)((const char*)(gbase) + (voff)[_i]), (LAS unsigned*)(lds + (bufoff) + ldsw + _i * 8192), 16, 0, 0); } while (0)
; #define PG8_LDA(dst, b, h) do { _Pragma("unroll") for (int m = 0; m < 4; ++m) _Pragma("unroll") for (int k = 0; k < 2; ++k) dst[m][k] = *(const LAS bf16x8*)(lds + PG8_SA(b, h) + aoff + m * 2048 + k * 1024); } while (0)
; #define PG8_LDB(dst, b, h) do { _Pragma("unroll") for (int n = 0; n < 2; ++n) _Pragma("unroll") for (int k = 0; k < 2; ++k) dst[n][k] = *(const LAS bf16x8*)(lds + PG8_SB(b, h) + boff + n * 2048 + k * 1024); } while (0)
; #define PG8_MMA(ai, bj, At, Bt) do { __builtin_amdgcn_s_setprio(1); _Pragma("unroll") for (int m = 0; m < 4; ++m) _Pragma("unroll") for (int n = 0; n < 2; ++n) _Pragma("unroll") for (int k = 0; k < 2; ++k) \
;         acc[ai][bj][m][n] = __builtin_amdgcn_mfma_f32_16x16x32_bf16(Bt[n][k], At[m][k], acc[ai][bj][m][n], 0, 0, 0); __builtin_amdgcn_s_setprio(0); } while (0)
; #define PG8_WAIT_V(n) asm volatile("s_waitcnt vmcnt(" #n ")" ::: "memory")
; #define PG8_WAIT_L(n) asm volatile("s_waitcnt lgkmcnt(" #n ")" ::: "memory")
; #define PG8_BAR __builtin_amdgcn_s_barrier()
; #define PG8_SCHED __builtin_amdgcn_sched_barrier(0)
; template <class Epi, class Sched>
; __device__ __forceinline__ void gemm_phase(const int tid, LAS unsigned char* lds, const Gemm g, const Sched& S, const Epi& E) {
;     ...
;             const bool last = (t == nt - 2);
;             const char* a1 = cA + (size_t)(t + 1) * kstepA;
;             const char* a2 = last ? nA : cA + (size_t)(t + 2) * kstepA; const char* b2 = last ? nB : cB + (size_t)(t + 2) * kstepB;
;             const char* a3 = a2 + kstepA; const char* b3 = b2 + kstepB;
;             PG8_LDB(B0, 0, 0); PG8_LDB(B1, 0, 1); PG8_SCHED; PG8_LDA(At, 0, 0); PG8_STAGE(PG8_SA(1, 1), a1 + hstepA, voffA);
;             PG8_WAIT_V(8); PG8_WAIT_L(0); PG8_BAR; PG8_MMA(0, 0, At, B0); PG8_MMA(0, 1, At, B1); PG8_BAR; PG8_SCHED;
;             PG8_LDA(At, 0, 1); PG8_STAGE(PG8_SB(0, 0), b2, voffB); PG8_STAGE(PG8_SB(0, 1), b2 + hstepB, voffB); PG8_STAGE(PG8_SA(0, 0), a2, voffA);
;             PG8_WAIT_V(8); PG8_WAIT_L(0); PG8_BAR; PG8_MMA(1, 0, At, B0); PG8_MMA(1, 1, At, B1); PG8_BAR; PG8_SCHED;
.LBB0_404:
	s_add_u32 s18, s6, 0xffe00080
	s_addc_u32 s19, s7, -1
	s_add_i32 s61, 16, 0x10000
	s_cmp_eq_u32 s60, 8
	s_cselect_b32 s21, s13, s19
	s_cselect_b32 s20, s57, s18
	s_cselect_b32 s19, s15, s59
	s_cselect_b32 s18, s14, s58
	s_add_i32 s64, 16, 0x14000
	v_add_u32_e32 v156, s61, v141
	v_add_u32_e32 v172, s64, v141
	ds_read_b128 v[144:147], v156
	ds_read_b128 v[148:151], v156 offset:1024
	ds_read_b128 v[152:155], v156 offset:2048
	ds_read_b128 v[156:159], v156 offset:3072
	ds_read_b128 v[160:163], v172
	ds_read_b128 v[164:167], v172 offset:1024
	ds_read_b128 v[168:171], v172 offset:2048
	ds_read_b128 v[172:175], v172 offset:3072
	s_add_i32 m0, s9, 0xc000
	ds_read_b128 v[176:179], v143
	ds_read_b128 v[180:183], v143 offset:1024
	ds_read_b128 v[184:187], v143 offset:2048
	ds_read_b128 v[188:191], v143 offset:3072
	ds_read_b128 v[204:207], v143 offset:4096
	ds_read_b128 v[208:211], v143 offset:5120
	ds_read_b128 v[212:215], v143 offset:6144
	ds_read_b128 v[216:219], v143 offset:7168
	global_load_lds_dwordx4 v138, s[6:7]
	s_add_i32 m0, s9, 0xe000
	s_nop 0
	global_load_lds_dwordx4 v136, s[6:7]
	s_waitcnt vmcnt(8)
	s_waitcnt lgkmcnt(0)
	s_barrier
	s_waitcnt lgkmcnt(0)
	v_mfma_f32_16x16x32_bf16 v[126:129], v[144:147], v[176:179], v[126:129]
	v_mfma_f32_16x16x32_bf16 v[122:125], v[152:155], v[176:179], v[122:125]
	v_mfma_f32_16x16x32_bf16 v[118:121], v[144:147], v[184:187], v[118:121]
	v_mfma_f32_16x16x32_bf16 v[114:117], v[152:155], v[184:187], v[114:117]
	v_mfma_f32_16x16x32_bf16 v[102:105], v[144:147], v[204:207], v[102:105]
	v_mfma_f32_16x16x32_bf16 v[98:101], v[152:155], v[204:207], v[98:101]
	v_mfma_f32_16x16x32_bf16 v[86:89], v[144:147], v[212:215], v[86:89]
	v_mfma_f32_16x16x32_bf16 v[82:85], v[152:155], v[212:215], v[82:85]
	v_mfma_f32_16x16x32_bf16 v[126:129], v[148:151], v[180:183], v[126:129]
	v_mfma_f32_16x16x32_bf16 v[122:125], v[156:159], v[180:183], v[122:125]
	v_mfma_f32_16x16x32_bf16 v[118:121], v[148:151], v[188:191], v[118:121]
	v_mfma_f32_16x16x32_bf16 v[114:117], v[156:159], v[188:191], v[114:117]
	v_mfma_f32_16x16x32_bf16 v[102:105], v[148:151], v[208:211], v[102:105]
	v_mfma_f32_16x16x32_bf16 v[98:101], v[156:159], v[208:211], v[98:101]
	v_mfma_f32_16x16x32_bf16 v[86:89], v[148:151], v[216:219], v[86:89]
	v_mfma_f32_16x16x32_bf16 v[82:85], v[156:159], v[216:219], v[82:85]
	v_mfma_f32_16x16x32_bf16 v[110:113], v[160:163], v[176:179], v[110:113]
	v_mfma_f32_16x16x32_bf16 v[106:109], v[168:171], v[176:179], v[106:109]
	v_mfma_f32_16x16x32_bf16 v[94:97], v[160:163], v[184:187], v[94:97]
	v_mfma_f32_16x16x32_bf16 v[90:93], v[168:171], v[184:187], v[90:93]
	v_mfma_f32_16x16x32_bf16 v[78:81], v[160:163], v[204:207], v[78:81]
	v_mfma_f32_16x16x32_bf16 v[74:77], v[168:171], v[204:207], v[74:77]
	v_mfma_f32_16x16x32_bf16 v[70:73], v[160:163], v[212:215], v[70:73]
	v_mfma_f32_16x16x32_bf16 v[66:69], v[168:171], v[212:215], v[66:69]
	v_mfma_f32_16x16x32_bf16 v[110:113], v[164:167], v[180:183], v[110:113]
	v_mfma_f32_16x16x32_bf16 v[106:109], v[172:175], v[180:183], v[106:109]
	v_mfma_f32_16x16x32_bf16 v[94:97], v[164:167], v[188:191], v[94:97]
	v_mfma_f32_16x16x32_bf16 v[90:93], v[172:175], v[188:191], v[90:93]
	v_mfma_f32_16x16x32_bf16 v[78:81], v[164:167], v[208:211], v[78:81]
	v_mfma_f32_16x16x32_bf16 v[74:77], v[172:175], v[208:211], v[74:77]
	v_mfma_f32_16x16x32_bf16 v[70:73], v[164:167], v[216:219], v[70:73]
	v_mfma_f32_16x16x32_bf16 v[66:69], v[172:175], v[216:219], v[66:69]
	s_barrier
	s_add_i32 s61, s61, s28
	s_mov_b32 m0, s61
	ds_read_b128 v[176:179], v143 offset:16384
	ds_read_b128 v[180:183], v143 offset:17408
	ds_read_b128 v[184:187], v143 offset:18432
	ds_read_b128 v[188:191], v143 offset:19456
	ds_read_b128 v[204:207], v143 offset:20480
	ds_read_b128 v[208:211], v143 offset:21504
	ds_read_b128 v[212:215], v143 offset:22528
	ds_read_b128 v[216:219], v143 offset:23552
	global_load_lds_dwordx4 v134, s[18:19]
	s_add_i32 m0, s61, 0x2000
	s_add_u32 s62, s18, 0x4000
	s_addc_u32 s63, s19, 0
	s_add_i32 s61, s64, s28
	global_load_lds_dwordx4 v130, s[18:19]
	s_mov_b32 m0, s61
	v_lshl_add_u64 v[220:221], s[20:21], 0, v[132:133]
	global_load_lds_dwordx4 v134, s[62:63]
	s_add_i32 m0, s61, 0x2000
	s_nop 0
	global_load_lds_dwordx4 v130, s[62:63]
	v_lshl_add_u64 v[192:193], s[20:21], 0, v[0:1]
	s_mov_b32 m0, s9
	s_nop 0
	global_load_lds_dwordx4 v[192:193], off
	s_mov_b32 m0, s30
	s_nop 0
	global_load_lds_dwordx4 v[220:221], off
	s_waitcnt vmcnt(8)
	s_waitcnt lgkmcnt(0)
	s_barrier
	s_waitcnt lgkmcnt(0)
	v_mfma_f32_16x16x32_bf16 v[62:65], v[144:147], v[176:179], v[62:65]
	v_mfma_f32_16x16x32_bf16 v[58:61], v[152:155], v[176:179], v[58:61]
	v_mfma_f32_16x16x32_bf16 v[54:57], v[144:147], v[184:187], v[54:57]
	v_mfma_f32_16x16x32_bf16 v[50:53], v[152:155], v[184:187], v[50:53]
	v_mfma_f32_16x16x32_bf16 v[38:41], v[144:147], v[204:207], v[38:41]
	v_mfma_f32_16x16x32_bf16 v[34:37], v[152:155], v[204:207], v[34:37]
	v_mfma_f32_16x16x32_bf16 v[22:25], v[144:147], v[212:215], v[22:25]
	v_mfma_f32_16x16x32_bf16 v[18:21], v[152:155], v[212:215], v[18:21]
	v_mfma_f32_16x16x32_bf16 v[62:65], v[148:151], v[180:183], v[62:65]
	v_mfma_f32_16x16x32_bf16 v[58:61], v[156:159], v[180:183], v[58:61]
	v_mfma_f32_16x16x32_bf16 v[54:57], v[148:151], v[188:191], v[54:57]
	v_mfma_f32_16x16x32_bf16 v[50:53], v[156:159], v[188:191], v[50:53]
	v_mfma_f32_16x16x32_bf16 v[38:41], v[148:151], v[208:211], v[38:41]
	v_mfma_f32_16x16x32_bf16 v[34:37], v[156:159], v[208:211], v[34:37]
	v_mfma_f32_16x16x32_bf16 v[22:25], v[148:151], v[216:219], v[22:25]
	v_mfma_f32_16x16x32_bf16 v[18:21], v[156:159], v[216:219], v[18:21]
	v_mfma_f32_16x16x32_bf16 v[46:49], v[160:163], v[176:179], v[46:49]
	v_mfma_f32_16x16x32_bf16 v[42:45], v[168:171], v[176:179], v[42:45]
	v_mfma_f32_16x16x32_bf16 v[30:33], v[160:163], v[184:187], v[30:33]
	v_mfma_f32_16x16x32_bf16 v[26:29], v[168:171], v[184:187], v[26:29]
	v_mfma_f32_16x16x32_bf16 v[14:17], v[160:163], v[204:207], v[14:17]
	v_mfma_f32_16x16x32_bf16 v[10:13], v[168:171], v[204:207], v[10:13]
	v_mfma_f32_16x16x32_bf16 v[6:9], v[160:163], v[212:215], v[6:9]
	v_mfma_f32_16x16x32_bf16 v[2:5], v[168:171], v[212:215], v[2:5]
	v_mfma_f32_16x16x32_bf16 v[46:49], v[164:167], v[180:183], v[46:49]
	v_mfma_f32_16x16x32_bf16 v[42:45], v[172:175], v[180:183], v[42:45]
	v_mfma_f32_16x16x32_bf16 v[30:33], v[164:167], v[188:191], v[30:33]
	v_mfma_f32_16x16x32_bf16 v[26:29], v[172:175], v[188:191], v[26:29]
	v_mfma_f32_16x16x32_bf16 v[14:17], v[164:167], v[208:211], v[14:17]
	v_mfma_f32_16x16x32_bf16 v[10:13], v[172:175], v[208:211], v[10:13]
	v_mfma_f32_16x16x32_bf16 v[6:9], v[164:167], v[216:219], v[6:9]
	v_mfma_f32_16x16x32_bf16 v[2:5], v[172:175], v[216:219], v[2:5]
	s_barrier
; #define PG8_STAGE(bufoff, gbase, voff) do { _Pragma("unroll") for (int _i = 0; _i < 2; ++_i) \
;         __builtin_amdgcn_global_load_lds((const unsigned*)((const char*)(gbase) + (voff)[_i]), (LAS unsigned*)(lds + (bufoff) + ldsw + _i * 8192), 16, 0, 0); } while (0)
; #define PG8_LDA(dst, b, h) do { _Pragma("unroll") for (int m = 0; m < 4; ++m) _Pragma("unroll") for (int k = 0; k < 2; ++k) dst[m][k] = *(const LAS bf16x8*)(lds + PG8_SA(b, h) + aoff + m * 2048 + k * 1024); } while (0)
; #define PG8_LDB(dst, b, h) do { _Pragma("unroll") for (int n = 0; n < 2; ++n) _Pragma("unroll") for (int k = 0; k < 2; ++k) dst[n][k] = *(const LAS bf16x8*)(lds + PG8_SB(b, h) + boff + n * 2048 + k * 1024); } while (0)
; #define PG8_MMA(ai, bj, At, Bt) do { __builtin_amdgcn_s_setprio(1); _Pragma("unroll") for (int m = 0; m < 4; ++m) _Pragma("unroll") for (int n = 0; n < 2; ++n) _Pragma("unroll") for (int k = 0; k < 2; ++k) \
;         acc[ai][bj][m][n] = __builtin_amdgcn_mfma_f32_16x16x32_bf16(Bt[n][k], At[m][k], acc[ai][bj][m][n], 0, 0, 0); __builtin_amdgcn_s_setprio(0); } while (0)
; #define PG8_WAIT_V(n) asm volatile("s_waitcnt vmcnt(" #n ")" ::: "memory")
; #define PG8_WAIT_L(n) asm volatile("s_waitcnt lgkmcnt(" #n ")" ::: "memory")
; #define PG8_BAR __builtin_amdgcn_s_barrier()
; #define PG8_SCHED __builtin_amdgcn_sched_barrier(0)
; template <class Epi, class Sched>
; __device__ __forceinline__ void gemm_phase(const int tid, LAS unsigned char* lds, const Gemm g, const Sched& S, const Epi& E) {
;     ...
;             PG8_LDB(B0, 1, 0); PG8_LDB(B1, 1, 1); PG8_SCHED; PG8_LDA(At, 1, 0); PG8_STAGE(PG8_SA(0, 1), a2 + hstepA, voffA);
;             PG8_WAIT_V(8); PG8_WAIT_L(0); PG8_BAR; PG8_MMA(0, 0, At, B0); PG8_MMA(0, 1, At, B1); PG8_BAR; PG8_SCHED;
;             PG8_LDA(At, 1, 1); PG8_STAGE(PG8_SB(1, 0), b3, voffB); PG8_STAGE(PG8_SB(1, 1), b3 + hstepB, voffB); PG8_STAGE(PG8_SA(1, 0), a3, voffA);
;             PG8_WAIT_V(8); PG8_WAIT_L(0); PG8_BAR; PG8_MMA(1, 0, At, B0); PG8_MMA(1, 1, At, B1); PG8_BAR; PG8_SCHED;
;         }
;         if (wr == 0) PG8_BAR;
	s_add_i32 s61, 16, 0x18000
	s_add_i32 s62, 16, 0x1c000
	v_add_u32_e32 v156, s61, v141
	v_add_u32_e32 v172, s62, v141
	ds_read_b128 v[144:147], v156
	ds_read_b128 v[148:151], v156 offset:1024
	ds_read_b128 v[152:155], v156 offset:2048
	ds_read_b128 v[156:159], v156 offset:3072
	ds_read_b128 v[160:163], v172
	ds_read_b128 v[164:167], v172 offset:1024
	ds_read_b128 v[168:171], v172 offset:2048
	ds_read_b128 v[172:175], v172 offset:3072
	s_add_u32 s20, s20, 0x200000
	s_addc_u32 s21, s21, 0
	s_mov_b32 m0, s31
	ds_read_b128 v[176:179], v143 offset:32768
	ds_read_b128 v[180:183], v143 offset:33792
	ds_read_b128 v[184:187], v143 offset:34816
	ds_read_b128 v[188:191], v143 offset:35840
	ds_read_b128 v[204:207], v143 offset:36864
	ds_read_b128 v[208:211], v143 offset:37888
	ds_read_b128 v[212:215], v143 offset:38912
	ds_read_b128 v[216:219], v143 offset:39936
	global_load_lds_dwordx4 v0, s[20:21]
	s_mov_b32 m0, s34
	s_nop 0
	global_load_lds_dwordx4 v132, s[20:21]
	s_waitcnt vmcnt(8)
	s_waitcnt lgkmcnt(0)
	s_barrier
	s_waitcnt lgkmcnt(0)
	v_mfma_f32_16x16x32_bf16 v[126:129], v[144:147], v[176:179], v[126:129]
	v_mfma_f32_16x16x32_bf16 v[122:125], v[152:155], v[176:179], v[122:125]
	v_mfma_f32_16x16x32_bf16 v[118:121], v[144:147], v[184:187], v[118:121]
	v_mfma_f32_16x16x32_bf16 v[114:117], v[152:155], v[184:187], v[114:117]
	v_mfma_f32_16x16x32_bf16 v[102:105], v[144:147], v[204:207], v[102:105]
	v_mfma_f32_16x16x32_bf16 v[98:101], v[152:155], v[204:207], v[98:101]
	v_mfma_f32_16x16x32_bf16 v[86:89], v[144:147], v[212:215], v[86:89]
	v_mfma_f32_16x16x32_bf16 v[82:85], v[152:155], v[212:215], v[82:85]
	v_mfma_f32_16x16x32_bf16 v[126:129], v[148:151], v[180:183], v[126:129]
	v_mfma_f32_16x16x32_bf16 v[122:125], v[156:159], v[180:183], v[122:125]
	v_mfma_f32_16x16x32_bf16 v[118:121], v[148:151], v[188:191], v[118:121]
	v_mfma_f32_16x16x32_bf16 v[114:117], v[156:159], v[188:191], v[114:117]
	v_mfma_f32_16x16x32_bf16 v[102:105], v[148:151], v[208:211], v[102:105]
	v_mfma_f32_16x16x32_bf16 v[98:101], v[156:159], v[208:211], v[98:101]
	v_mfma_f32_16x16x32_bf16 v[86:89], v[148:151], v[216:219], v[86:89]
	v_mfma_f32_16x16x32_bf16 v[82:85], v[156:159], v[216:219], v[82:85]
	v_mfma_f32_16x16x32_bf16 v[110:113], v[160:163], v[176:179], v[110:113]
	v_mfma_f32_16x16x32_bf16 v[106:109], v[168:171], v[176:179], v[106:109]
	v_mfma_f32_16x16x32_bf16 v[94:97], v[160:163], v[184:187], v[94:97]
	v_mfma_f32_16x16x32_bf16 v[90:93], v[168:171], v[184:187], v[90:93]
	v_mfma_f32_16x16x32_bf16 v[78:81], v[160:163], v[204:207], v[78:81]
	v_mfma_f32_16x16x32_bf16 v[74:77], v[168:171], v[204:207], v[74:77]
	v_mfma_f32_16x16x32_bf16 v[70:73], v[160:163], v[212:215], v[70:73]
	v_mfma_f32_16x16x32_bf16 v[66:69], v[168:171], v[212:215], v[66:69]
	v_mfma_f32_16x16x32_bf16 v[110:113], v[164:167], v[180:183], v[110:113]
	v_mfma_f32_16x16x32_bf16 v[106:109], v[172:175], v[180:183], v[106:109]
	v_mfma_f32_16x16x32_bf16 v[94:97], v[164:167], v[188:191], v[94:97]
	v_mfma_f32_16x16x32_bf16 v[90:93], v[172:175], v[188:191], v[90:93]
	v_mfma_f32_16x16x32_bf16 v[78:81], v[164:167], v[208:211], v[78:81]
	v_mfma_f32_16x16x32_bf16 v[74:77], v[172:175], v[208:211], v[74:77]
	v_mfma_f32_16x16x32_bf16 v[70:73], v[164:167], v[216:219], v[70:73]
	v_mfma_f32_16x16x32_bf16 v[66:69], v[172:175], v[216:219], v[66:69]
	s_barrier
	s_add_u32 s20, s18, 0x8000
	s_addc_u32 s21, s19, 0
	s_add_i32 s61, s61, s28
	s_mov_b32 m0, s61
	ds_read_b128 v[176:179], v143 offset:49152
	ds_read_b128 v[180:183], v143 offset:50176
	ds_read_b128 v[184:187], v143 offset:51200
	ds_read_b128 v[188:191], v143 offset:52224
	ds_read_b128 v[204:207], v143 offset:53248
	ds_read_b128 v[208:211], v143 offset:54272
	ds_read_b128 v[212:215], v143 offset:55296
	ds_read_b128 v[216:219], v143 offset:56320
	global_load_lds_dwordx4 v134, s[20:21]
	s_add_i32 m0, s61, 0x2000
	s_add_u32 s18, s18, 0xc000
	s_addc_u32 s19, s19, 0
	global_load_lds_dwordx4 v130, s[20:21]
	s_add_i32 s20, s62, s28
	s_mov_b32 m0, s20
	v_lshl_add_u64 v[192:193], v[192:193], 0, s[88:89]
	global_load_lds_dwordx4 v134, s[18:19]
	s_add_i32 m0, s20, 0x2000
	s_nop 0
	global_load_lds_dwordx4 v130, s[18:19]
	s_mov_b32 m0, s35
	s_nop 0
	global_load_lds_dwordx4 v[192:193], off
	v_lshl_add_u64 v[192:193], v[220:221], 0, s[88:89]
	s_mov_b32 m0, s52
	s_nop 0
	global_load_lds_dwordx4 v[192:193], off
	s_waitcnt vmcnt(8)
	s_waitcnt lgkmcnt(0)
	s_barrier
	s_waitcnt lgkmcnt(0)
	v_mfma_f32_16x16x32_bf16 v[62:65], v[144:147], v[176:179], v[62:65]
	v_mfma_f32_16x16x32_bf16 v[58:61], v[152:155], v[176:179], v[58:61]
	v_mfma_f32_16x16x32_bf16 v[54:57], v[144:147], v[184:187], v[54:57]
	v_mfma_f32_16x16x32_bf16 v[50:53], v[152:155], v[184:187], v[50:53]
	v_mfma_f32_16x16x32_bf16 v[38:41], v[144:147], v[204:207], v[38:41]
	v_mfma_f32_16x16x32_bf16 v[34:37], v[152:155], v[204:207], v[34:37]
	v_mfma_f32_16x16x32_bf16 v[22:25], v[144:147], v[212:215], v[22:25]
	v_mfma_f32_16x16x32_bf16 v[18:21], v[152:155], v[212:215], v[18:21]
	v_mfma_f32_16x16x32_bf16 v[62:65], v[148:151], v[180:183], v[62:65]
	v_mfma_f32_16x16x32_bf16 v[58:61], v[156:159], v[180:183], v[58:61]
	v_mfma_f32_16x16x32_bf16 v[54:57], v[148:151], v[188:191], v[54:57]
	v_mfma_f32_16x16x32_bf16 v[50:53], v[156:159], v[188:191], v[50:53]
	v_mfma_f32_16x16x32_bf16 v[38:41], v[148:151], v[208:211], v[38:41]
	v_mfma_f32_16x16x32_bf16 v[34:37], v[156:159], v[208:211], v[34:37]
	v_mfma_f32_16x16x32_bf16 v[22:25], v[148:151], v[216:219], v[22:25]
	v_mfma_f32_16x16x32_bf16 v[18:21], v[156:159], v[216:219], v[18:21]
	v_mfma_f32_16x16x32_bf16 v[46:49], v[160:163], v[176:179], v[46:49]
	v_mfma_f32_16x16x32_bf16 v[42:45], v[168:171], v[176:179], v[42:45]
	v_mfma_f32_16x16x32_bf16 v[30:33], v[160:163], v[184:187], v[30:33]
	v_mfma_f32_16x16x32_bf16 v[26:29], v[168:171], v[184:187], v[26:29]
	v_mfma_f32_16x16x32_bf16 v[14:17], v[160:163], v[204:207], v[14:17]
	v_mfma_f32_16x16x32_bf16 v[10:13], v[168:171], v[204:207], v[10:13]
	v_mfma_f32_16x16x32_bf16 v[6:9], v[160:163], v[212:215], v[6:9]
	v_mfma_f32_16x16x32_bf16 v[2:5], v[168:171], v[212:215], v[2:5]
	v_mfma_f32_16x16x32_bf16 v[46:49], v[164:167], v[180:183], v[46:49]
	v_mfma_f32_16x16x32_bf16 v[42:45], v[172:175], v[180:183], v[42:45]
	v_mfma_f32_16x16x32_bf16 v[30:33], v[164:167], v[188:191], v[30:33]
	v_mfma_f32_16x16x32_bf16 v[26:29], v[172:175], v[188:191], v[26:29]
	v_mfma_f32_16x16x32_bf16 v[14:17], v[164:167], v[208:211], v[14:17]
	v_mfma_f32_16x16x32_bf16 v[10:13], v[172:175], v[208:211], v[10:13]
	v_mfma_f32_16x16x32_bf16 v[6:9], v[164:167], v[216:219], v[6:9]
	v_mfma_f32_16x16x32_bf16 v[2:5], v[172:175], v[216:219], v[2:5]
	s_barrier
	s_add_i32 s60, s60, 2
	s_add_u32 s58, s58, 0x10000
	s_addc_u32 s59, s59, 0
	s_add_u32 s6, s6, 0x100
	s_addc_u32 s7, s7, 0
	s_cmp_gt_u32 s60, 9
	s_cbranch_scc0 .LBB0_404
	s_and_b64 vcc, exec, s[10:11]
	s_cbranch_vccz .LBB0_407
	s_barrier

; #define PG8_STAGE(bufoff, gbase, voff) do { _Pragma("unroll") for (int _i = 0; _i < 2; ++_i) \
;         __builtin_amdgcn_global_load_lds((const unsigned*)((const char*)(gbase) + (voff)[_i]), (LAS unsigned*)(lds + (bufoff) + ldsw + _i * 8192), 16, 0, 0); } while (0)
; #define PG8_LDA(dst, b, h) do { _Pragma("unroll") for (int m = 0; m < 4; ++m) _Pragma("unroll") for (int k = 0; k < 2; ++k) dst[m][k] = *(const LAS bf16x8*)(lds + PG8_SA(b, h) + aoff + m * 2048 + k * 1024); } while (0)
; #define PG8_LDB(dst, b, h) do { _Pragma("unroll") for (int n = 0; n < 2; ++n) _Pragma("unroll") for (int k = 0; k < 2; ++k) dst[n][k] = *(const LAS bf16x8*)(lds + PG8_SB(b, h) + boff + n * 2048 + k * 1024); } while (0)
; #define PG8_MMA(ai, bj, At, Bt) do { __builtin_amdgcn_s_setprio(1); _Pragma("unroll") for (int m = 0; m < 4; ++m) _Pragma("unroll") for (int n = 0; n < 2; ++n) _Pragma("unroll") for (int k = 0; k < 2; ++k) \
;         acc[ai][bj][m][n] = __builtin_amdgcn_mfma_f32_16x16x32_bf16(Bt[n][k], At[m][k], acc[ai][bj][m][n], 0, 0, 0); __builtin_amdgcn_s_setprio(0); } while (0)
; #define PG8_WAIT_V(n) asm volatile("s_waitcnt vmcnt(" #n ")" ::: "memory")
; #define PG8_WAIT_L(n) asm volatile("s_waitcnt lgkmcnt(" #n ")" ::: "memory")
; #define PG8_BAR __builtin_amdgcn_s_barrier()
; #define PG8_SCHED __builtin_amdgcn_sched_barrier(0)
; template <class Epi, class Sched>
; __device__ __forceinline__ void gemm_phase(const int tid, LAS unsigned char* lds, const Gemm g, const Sched& S, const Epi& E) {
;     ...
;             const bool last = (t == nt - 2);
;             const char* a1 = cA + (size_t)(t + 1) * kstepA;
;             const char* a2 = last ? nA : cA + (size_t)(t + 2) * kstepA; const char* b2 = last ? nB : cB + (size_t)(t + 2) * kstepB;
;             const char* a3 = a2 + kstepA; const char* b3 = b2 + kstepB;
;             PG8_LDB(B0, 0, 0); PG8_LDB(B1, 0, 1); PG8_SCHED; PG8_LDA(At, 0, 0); PG8_STAGE(PG8_SA(1, 1), a1 + hstepA, voffA);
;             PG8_WAIT_V(8); PG8_WAIT_L(0); PG8_BAR; PG8_MMA(0, 0, At, B0); PG8_MMA(0, 1, At, B1); PG8_BAR; PG8_SCHED;
;             PG8_LDA(At, 0, 1); PG8_STAGE(PG8_SB(0, 0), b2, voffB); PG8_STAGE(PG8_SB(0, 1), b2 + hstepB, voffB); PG8_STAGE(PG8_SA(0, 0), a2, voffA);
;             PG8_WAIT_V(8); PG8_WAIT_L(0); PG8_BAR; PG8_MMA(1, 0, At, B0); PG8_MMA(1, 1, At, B1); PG8_BAR; PG8_SCHED;
.LBB0_428:
	s_add_u32 s20, s18, 0xffe00080
	s_addc_u32 s21, s19, -1
	s_add_i32 s63, 16, 0x10000
	s_cmp_eq_u32 s62, 4
	s_cselect_b32 s23, s13, s21
	s_cselect_b32 s22, s58, s20
	s_cselect_b32 s21, s11, s61
	s_cselect_b32 s20, s59, s60
	s_add_i32 s66, 16, 0x14000
	v_add_u32_e32 v156, s63, v141
	v_add_u32_e32 v172, s66, v141
	ds_read_b128 v[144:147], v156
	ds_read_b128 v[148:151], v156 offset:1024
	ds_read_b128 v[152:155], v156 offset:2048
	ds_read_b128 v[156:159], v156 offset:3072
	ds_read_b128 v[160:163], v172
	ds_read_b128 v[164:167], v172 offset:1024
	ds_read_b128 v[168:171], v172 offset:2048
	ds_read_b128 v[172:175], v172 offset:3072
	s_add_i32 m0, s9, 0xc000
	ds_read_b128 v[176:179], v143
	ds_read_b128 v[180:183], v143 offset:1024
	ds_read_b128 v[184:187], v143 offset:2048
	ds_read_b128 v[188:191], v143 offset:3072
	ds_read_b128 v[204:207], v143 offset:4096
	ds_read_b128 v[208:211], v143 offset:5120
	ds_read_b128 v[212:215], v143 offset:6144
	ds_read_b128 v[216:219], v143 offset:7168
	global_load_lds_dwordx4 v138, s[18:19]
	s_add_i32 m0, s9, 0xe000
	s_nop 0
	global_load_lds_dwordx4 v136, s[18:19]
	s_waitcnt vmcnt(8)
	s_waitcnt lgkmcnt(0)
	s_barrier
	s_waitcnt lgkmcnt(0)
	v_mfma_f32_16x16x32_bf16 v[126:129], v[144:147], v[176:179], v[126:129]
	v_mfma_f32_16x16x32_bf16 v[122:125], v[152:155], v[176:179], v[122:125]
	v_mfma_f32_16x16x32_bf16 v[118:121], v[144:147], v[184:187], v[118:121]
	v_mfma_f32_16x16x32_bf16 v[114:117], v[152:155], v[184:187], v[114:117]
	v_mfma_f32_16x16x32_bf16 v[102:105], v[144:147], v[204:207], v[102:105]
	v_mfma_f32_16x16x32_bf16 v[98:101], v[152:155], v[204:207], v[98:101]
	v_mfma_f32_16x16x32_bf16 v[86:89], v[144:147], v[212:215], v[86:89]
	v_mfma_f32_16x16x32_bf16 v[82:85], v[152:155], v[212:215], v[82:85]
	v_mfma_f32_16x16x32_bf16 v[126:129], v[148:151], v[180:183], v[126:129]
	v_mfma_f32_16x16x32_bf16 v[122:125], v[156:159], v[180:183], v[122:125]
	v_mfma_f32_16x16x32_bf16 v[118:121], v[148:151], v[188:191], v[118:121]
	v_mfma_f32_16x16x32_bf16 v[114:117], v[156:159], v[188:191], v[114:117]
	v_mfma_f32_16x16x32_bf16 v[102:105], v[148:151], v[208:211], v[102:105]
	v_mfma_f32_16x16x32_bf16 v[98:101], v[156:159], v[208:211], v[98:101]
	v_mfma_f32_16x16x32_bf16 v[86:89], v[148:151], v[216:219], v[86:89]
	v_mfma_f32_16x16x32_bf16 v[82:85], v[156:159], v[216:219], v[82:85]
	v_mfma_f32_16x16x32_bf16 v[110:113], v[160:163], v[176:179], v[110:113]
	v_mfma_f32_16x16x32_bf16 v[106:109], v[168:171], v[176:179], v[106:109]
	v_mfma_f32_16x16x32_bf16 v[94:97], v[160:163], v[184:187], v[94:97]
	v_mfma_f32_16x16x32_bf16 v[90:93], v[168:171], v[184:187], v[90:93]
	v_mfma_f32_16x16x32_bf16 v[78:81], v[160:163], v[204:207], v[78:81]
	v_mfma_f32_16x16x32_bf16 v[74:77], v[168:171], v[204:207], v[74:77]
	v_mfma_f32_16x16x32_bf16 v[70:73], v[160:163], v[212:215], v[70:73]
	v_mfma_f32_16x16x32_bf16 v[66:69], v[168:171], v[212:215], v[66:69]
	v_mfma_f32_16x16x32_bf16 v[110:113], v[164:167], v[180:183], v[110:113]
	v_mfma_f32_16x16x32_bf16 v[106:109], v[172:175], v[180:183], v[106:109]
	v_mfma_f32_16x16x32_bf16 v[94:97], v[164:167], v[188:191], v[94:97]
	v_mfma_f32_16x16x32_bf16 v[90:93], v[172:175], v[188:191], v[90:93]
	v_mfma_f32_16x16x32_bf16 v[78:81], v[164:167], v[208:211], v[78:81]
	v_mfma_f32_16x16x32_bf16 v[74:77], v[172:175], v[208:211], v[74:77]
	v_mfma_f32_16x16x32_bf16 v[70:73], v[164:167], v[216:219], v[70:73]
	v_mfma_f32_16x16x32_bf16 v[66:69], v[172:175], v[216:219], v[66:69]
	s_barrier
	s_add_i32 s63, s63, s31
	s_mov_b32 m0, s63
	ds_read_b128 v[176:179], v143 offset:16384
	ds_read_b128 v[180:183], v143 offset:17408
	ds_read_b128 v[184:187], v143 offset:18432
	ds_read_b128 v[188:191], v143 offset:19456
	ds_read_b128 v[204:207], v143 offset:20480
	ds_read_b128 v[208:211], v143 offset:21504
	ds_read_b128 v[212:215], v143 offset:22528
	ds_read_b128 v[216:219], v143 offset:23552
	global_load_lds_dwordx4 v130, s[20:21]
	s_add_i32 m0, s63, 0x2000
	s_add_u32 s64, s20, 0x4000
	s_addc_u32 s65, s21, 0
	s_add_i32 s63, s66, s31
	global_load_lds_dwordx4 v134, s[20:21]
	s_mov_b32 m0, s63
	v_lshl_add_u64 v[220:221], s[22:23], 0, v[132:133]
	global_load_lds_dwordx4 v130, s[64:65]
	s_add_i32 m0, s63, 0x2000
	s_nop 0
	global_load_lds_dwordx4 v134, s[64:65]
	v_lshl_add_u64 v[192:193], s[22:23], 0, v[0:1]
	s_mov_b32 m0, s9
	s_nop 0
	global_load_lds_dwordx4 v[192:193], off
	s_mov_b32 m0, s34
	s_nop 0
	global_load_lds_dwordx4 v[220:221], off
	s_waitcnt vmcnt(8)
	s_waitcnt lgkmcnt(0)
	s_barrier
	s_waitcnt lgkmcnt(0)
	v_mfma_f32_16x16x32_bf16 v[62:65], v[144:147], v[176:179], v[62:65]
	v_mfma_f32_16x16x32_bf16 v[58:61], v[152:155], v[176:179], v[58:61]
	v_mfma_f32_16x16x32_bf16 v[54:57], v[144:147], v[184:187], v[54:57]
	v_mfma_f32_16x16x32_bf16 v[50:53], v[152:155], v[184:187], v[50:53]
	v_mfma_f32_16x16x32_bf16 v[38:41], v[144:147], v[204:207], v[38:41]
	v_mfma_f32_16x16x32_bf16 v[34:37], v[152:155], v[204:207], v[34:37]
	v_mfma_f32_16x16x32_bf16 v[22:25], v[144:147], v[212:215], v[22:25]
	v_mfma_f32_16x16x32_bf16 v[18:21], v[152:155], v[212:215], v[18:21]
	v_mfma_f32_16x16x32_bf16 v[62:65], v[148:151], v[180:183], v[62:65]
	v_mfma_f32_16x16x32_bf16 v[58:61], v[156:159], v[180:183], v[58:61]
	v_mfma_f32_16x16x32_bf16 v[54:57], v[148:151], v[188:191], v[54:57]
	v_mfma_f32_16x16x32_bf16 v[50:53], v[156:159], v[188:191], v[50:53]
	v_mfma_f32_16x16x32_bf16 v[38:41], v[148:151], v[208:211], v[38:41]
	v_mfma_f32_16x16x32_bf16 v[34:37], v[156:159], v[208:211], v[34:37]
	v_mfma_f32_16x16x32_bf16 v[22:25], v[148:151], v[216:219], v[22:25]
	v_mfma_f32_16x16x32_bf16 v[18:21], v[156:159], v[216:219], v[18:21]
	v_mfma_f32_16x16x32_bf16 v[46:49], v[160:163], v[176:179], v[46:49]
	v_mfma_f32_16x16x32_bf16 v[42:45], v[168:171], v[176:179], v[42:45]
	v_mfma_f32_16x16x32_bf16 v[30:33], v[160:163], v[184:187], v[30:33]
	v_mfma_f32_16x16x32_bf16 v[26:29], v[168:171], v[184:187], v[26:29]
	v_mfma_f32_16x16x32_bf16 v[14:17], v[160:163], v[204:207], v[14:17]
	v_mfma_f32_16x16x32_bf16 v[10:13], v[168:171], v[204:207], v[10:13]
	v_mfma_f32_16x16x32_bf16 v[6:9], v[160:163], v[212:215], v[6:9]
	v_mfma_f32_16x16x32_bf16 v[2:5], v[168:171], v[212:215], v[2:5]
	v_mfma_f32_16x16x32_bf16 v[46:49], v[164:167], v[180:183], v[46:49]
	v_mfma_f32_16x16x32_bf16 v[42:45], v[172:175], v[180:183], v[42:45]
	v_mfma_f32_16x16x32_bf16 v[30:33], v[164:167], v[188:191], v[30:33]
	v_mfma_f32_16x16x32_bf16 v[26:29], v[172:175], v[188:191], v[26:29]
	v_mfma_f32_16x16x32_bf16 v[14:17], v[164:167], v[208:211], v[14:17]
	v_mfma_f32_16x16x32_bf16 v[10:13], v[172:175], v[208:211], v[10:13]
	v_mfma_f32_16x16x32_bf16 v[6:9], v[164:167], v[216:219], v[6:9]
	v_mfma_f32_16x16x32_bf16 v[2:5], v[172:175], v[216:219], v[2:5]
	s_barrier
; #define PG8_STAGE(bufoff, gbase, voff) do { _Pragma("unroll") for (int _i = 0; _i < 2; ++_i) \
;         __builtin_amdgcn_global_load_lds((const unsigned*)((const char*)(gbase) + (voff)[_i]), (LAS unsigned*)(lds + (bufoff) + ldsw + _i * 8192), 16, 0, 0); } while (0)
; #define PG8_LDA(dst, b, h) do { _Pragma("unroll") for (int m = 0; m < 4; ++m) _Pragma("unroll") for (int k = 0; k < 2; ++k) dst[m][k] = *(const LAS bf16x8*)(lds + PG8_SA(b, h) + aoff + m * 2048 + k * 1024); } while (0)
; #define PG8_LDB(dst, b, h) do { _Pragma("unroll") for (int n = 0; n < 2; ++n) _Pragma("unroll") for (int k = 0; k < 2; ++k) dst[n][k] = *(const LAS bf16x8*)(lds + PG8_SB(b, h) + boff + n * 2048 + k * 1024); } while (0)
; #define PG8_MMA(ai, bj, At, Bt) do { __builtin_amdgcn_s_setprio(1); _Pragma("unroll") for (int m = 0; m < 4; ++m) _Pragma("unroll") for (int n = 0; n < 2; ++n) _Pragma("unroll") for (int k = 0; k < 2; ++k) \
;         acc[ai][bj][m][n] = __builtin_amdgcn_mfma_f32_16x16x32_bf16(Bt[n][k], At[m][k], acc[ai][bj][m][n], 0, 0, 0); __builtin_amdgcn_s_setprio(0); } while (0)
; #define PG8_WAIT_V(n) asm volatile("s_waitcnt vmcnt(" #n ")" ::: "memory")
; #define PG8_WAIT_L(n) asm volatile("s_waitcnt lgkmcnt(" #n ")" ::: "memory")
; #define PG8_BAR __builtin_amdgcn_s_barrier()
; #define PG8_SCHED __builtin_amdgcn_sched_barrier(0)
; template <class Epi, class Sched>
; __device__ __forceinline__ void gemm_phase(const int tid, LAS unsigned char* lds, const Gemm g, const Sched& S, const Epi& E) {
;     ...
;             PG8_LDB(B0, 1, 0); PG8_LDB(B1, 1, 1); PG8_SCHED; PG8_LDA(At, 1, 0); PG8_STAGE(PG8_SA(0, 1), a2 + hstepA, voffA);
;             PG8_WAIT_V(8); PG8_WAIT_L(0); PG8_BAR; PG8_MMA(0, 0, At, B0); PG8_MMA(0, 1, At, B1); PG8_BAR; PG8_SCHED;
;             PG8_LDA(At, 1, 1); PG8_STAGE(PG8_SB(1, 0), b3, voffB); PG8_STAGE(PG8_SB(1, 1), b3 + hstepB, voffB); PG8_STAGE(PG8_SA(1, 0), a3, voffA);
;             PG8_WAIT_V(8); PG8_WAIT_L(0); PG8_BAR; PG8_MMA(1, 0, At, B0); PG8_MMA(1, 1, At, B1); PG8_BAR; PG8_SCHED;
;         }
;         if (wr == 0) PG8_BAR;
	s_add_i32 s63, 16, 0x18000
	s_add_i32 s64, 16, 0x1c000
	v_add_u32_e32 v156, s63, v141
	v_add_u32_e32 v172, s64, v141
	ds_read_b128 v[144:147], v156
	ds_read_b128 v[148:151], v156 offset:1024
	ds_read_b128 v[152:155], v156 offset:2048
	ds_read_b128 v[156:159], v156 offset:3072
	ds_read_b128 v[160:163], v172
	ds_read_b128 v[164:167], v172 offset:1024
	ds_read_b128 v[168:171], v172 offset:2048
	ds_read_b128 v[172:175], v172 offset:3072
	s_add_u32 s22, s22, 0x200000
	s_addc_u32 s23, s23, 0
	s_mov_b32 m0, s35
	ds_read_b128 v[176:179], v143 offset:32768
	ds_read_b128 v[180:183], v143 offset:33792
	ds_read_b128 v[184:187], v143 offset:34816
	ds_read_b128 v[188:191], v143 offset:35840
	ds_read_b128 v[204:207], v143 offset:36864
	ds_read_b128 v[208:211], v143 offset:37888
	ds_read_b128 v[212:215], v143 offset:38912
	ds_read_b128 v[216:219], v143 offset:39936
	global_load_lds_dwordx4 v0, s[22:23]
	s_mov_b32 m0, s52
	s_nop 0
	global_load_lds_dwordx4 v132, s[22:23]
	s_waitcnt vmcnt(8)
	s_waitcnt lgkmcnt(0)
	s_barrier
	s_waitcnt lgkmcnt(0)
	v_mfma_f32_16x16x32_bf16 v[126:129], v[144:147], v[176:179], v[126:129]
	v_mfma_f32_16x16x32_bf16 v[122:125], v[152:155], v[176:179], v[122:125]
	v_mfma_f32_16x16x32_bf16 v[118:121], v[144:147], v[184:187], v[118:121]
	v_mfma_f32_16x16x32_bf16 v[114:117], v[152:155], v[184:187], v[114:117]
	v_mfma_f32_16x16x32_bf16 v[102:105], v[144:147], v[204:207], v[102:105]
	v_mfma_f32_16x16x32_bf16 v[98:101], v[152:155], v[204:207], v[98:101]
	v_mfma_f32_16x16x32_bf16 v[86:89], v[144:147], v[212:215], v[86:89]
	v_mfma_f32_16x16x32_bf16 v[82:85], v[152:155], v[212:215], v[82:85]
	v_mfma_f32_16x16x32_bf16 v[126:129], v[148:151], v[180:183], v[126:129]
	v_mfma_f32_16x16x32_bf16 v[122:125], v[156:159], v[180:183], v[122:125]
	v_mfma_f32_16x16x32_bf16 v[118:121], v[148:151], v[188:191], v[118:121]
	v_mfma_f32_16x16x32_bf16 v[114:117], v[156:159], v[188:191], v[114:117]
	v_mfma_f32_16x16x32_bf16 v[102:105], v[148:151], v[208:211], v[102:105]
	v_mfma_f32_16x16x32_bf16 v[98:101], v[156:159], v[208:211], v[98:101]
	v_mfma_f32_16x16x32_bf16 v[86:89], v[148:151], v[216:219], v[86:89]
	v_mfma_f32_16x16x32_bf16 v[82:85], v[156:159], v[216:219], v[82:85]
	v_mfma_f32_16x16x32_bf16 v[110:113], v[160:163], v[176:179], v[110:113]
	v_mfma_f32_16x16x32_bf16 v[106:109], v[168:171], v[176:179], v[106:109]
	v_mfma_f32_16x16x32_bf16 v[94:97], v[160:163], v[184:187], v[94:97]
	v_mfma_f32_16x16x32_bf16 v[90:93], v[168:171], v[184:187], v[90:93]
	v_mfma_f32_16x16x32_bf16 v[78:81], v[160:163], v[204:207], v[78:81]
	v_mfma_f32_16x16x32_bf16 v[74:77], v[168:171], v[204:207], v[74:77]
	v_mfma_f32_16x16x32_bf16 v[70:73], v[160:163], v[212:215], v[70:73]
	v_mfma_f32_16x16x32_bf16 v[66:69], v[168:171], v[212:215], v[66:69]
	v_mfma_f32_16x16x32_bf16 v[110:113], v[164:167], v[180:183], v[110:113]
	v_mfma_f32_16x16x32_bf16 v[106:109], v[172:175], v[180:183], v[106:109]
	v_mfma_f32_16x16x32_bf16 v[94:97], v[164:167], v[188:191], v[94:97]
	v_mfma_f32_16x16x32_bf16 v[90:93], v[172:175], v[188:191], v[90:93]
	v_mfma_f32_16x16x32_bf16 v[78:81], v[164:167], v[208:211], v[78:81]
	v_mfma_f32_16x16x32_bf16 v[74:77], v[172:175], v[208:211], v[74:77]
	v_mfma_f32_16x16x32_bf16 v[70:73], v[164:167], v[216:219], v[70:73]
	v_mfma_f32_16x16x32_bf16 v[66:69], v[172:175], v[216:219], v[66:69]
	s_barrier
	s_add_u32 s22, s20, 0x8000
	s_addc_u32 s23, s21, 0
	s_add_i32 s63, s63, s31
	s_mov_b32 m0, s63
	ds_read_b128 v[176:179], v143 offset:49152
	ds_read_b128 v[180:183], v143 offset:50176
	ds_read_b128 v[184:187], v143 offset:51200
	ds_read_b128 v[188:191], v143 offset:52224
	ds_read_b128 v[204:207], v143 offset:53248
	ds_read_b128 v[208:211], v143 offset:54272
	ds_read_b128 v[212:215], v143 offset:55296
	ds_read_b128 v[216:219], v143 offset:56320
	global_load_lds_dwordx4 v130, s[22:23]
	s_add_i32 m0, s63, 0x2000
	s_add_u32 s20, s20, 0xc000
	s_addc_u32 s21, s21, 0
	global_load_lds_dwordx4 v134, s[22:23]
	s_add_i32 s22, s64, s31
	s_mov_b32 m0, s22
	v_lshl_add_u64 v[192:193], v[192:193], 0, s[88:89]
	global_load_lds_dwordx4 v130, s[20:21]
	s_add_i32 m0, s22, 0x2000
	s_nop 0
	global_load_lds_dwordx4 v134, s[20:21]
	s_mov_b32 m0, s53
	s_nop 0
	global_load_lds_dwordx4 v[192:193], off
	v_lshl_add_u64 v[192:193], v[220:221], 0, s[88:89]
	s_mov_b32 m0, s54
	s_nop 0
	global_load_lds_dwordx4 v[192:193], off
	s_waitcnt vmcnt(8)
	s_waitcnt lgkmcnt(0)
	s_barrier
	s_waitcnt lgkmcnt(0)
	v_mfma_f32_16x16x32_bf16 v[62:65], v[144:147], v[176:179], v[62:65]
	v_mfma_f32_16x16x32_bf16 v[58:61], v[152:155], v[176:179], v[58:61]
	v_mfma_f32_16x16x32_bf16 v[54:57], v[144:147], v[184:187], v[54:57]
	v_mfma_f32_16x16x32_bf16 v[50:53], v[152:155], v[184:187], v[50:53]
	v_mfma_f32_16x16x32_bf16 v[38:41], v[144:147], v[204:207], v[38:41]
	v_mfma_f32_16x16x32_bf16 v[34:37], v[152:155], v[204:207], v[34:37]
	v_mfma_f32_16x16x32_bf16 v[22:25], v[144:147], v[212:215], v[22:25]
	v_mfma_f32_16x16x32_bf16 v[18:21], v[152:155], v[212:215], v[18:21]
	v_mfma_f32_16x16x32_bf16 v[62:65], v[148:151], v[180:183], v[62:65]
	v_mfma_f32_16x16x32_bf16 v[58:61], v[156:159], v[180:183], v[58:61]
	v_mfma_f32_16x16x32_bf16 v[54:57], v[148:151], v[188:191], v[54:57]
	v_mfma_f32_16x16x32_bf16 v[50:53], v[156:159], v[188:191], v[50:53]
	v_mfma_f32_16x16x32_bf16 v[38:41], v[148:151], v[208:211], v[38:41]
	v_mfma_f32_16x16x32_bf16 v[34:37], v[156:159], v[208:211], v[34:37]
	v_mfma_f32_16x16x32_bf16 v[22:25], v[148:151], v[216:219], v[22:25]
	v_mfma_f32_16x16x32_bf16 v[18:21], v[156:159], v[216:219], v[18:21]
	v_mfma_f32_16x16x32_bf16 v[46:49], v[160:163], v[176:179], v[46:49]
	v_mfma_f32_16x16x32_bf16 v[42:45], v[168:171], v[176:179], v[42:45]
	v_mfma_f32_16x16x32_bf16 v[30:33], v[160:163], v[184:187], v[30:33]
	v_mfma_f32_16x16x32_bf16 v[26:29], v[168:171], v[184:187], v[26:29]
	v_mfma_f32_16x16x32_bf16 v[14:17], v[160:163], v[204:207], v[14:17]
	v_mfma_f32_16x16x32_bf16 v[10:13], v[168:171], v[204:207], v[10:13]
	v_mfma_f32_16x16x32_bf16 v[6:9], v[160:163], v[212:215], v[6:9]
	v_mfma_f32_16x16x32_bf16 v[2:5], v[168:171], v[212:215], v[2:5]
	v_mfma_f32_16x16x32_bf16 v[46:49], v[164:167], v[180:183], v[46:49]
	v_mfma_f32_16x16x32_bf16 v[42:45], v[172:175], v[180:183], v[42:45]
	v_mfma_f32_16x16x32_bf16 v[30:33], v[164:167], v[188:191], v[30:33]
	v_mfma_f32_16x16x32_bf16 v[26:29], v[172:175], v[188:191], v[26:29]
	v_mfma_f32_16x16x32_bf16 v[14:17], v[164:167], v[208:211], v[14:17]
	v_mfma_f32_16x16x32_bf16 v[10:13], v[172:175], v[208:211], v[10:13]
	v_mfma_f32_16x16x32_bf16 v[6:9], v[164:167], v[216:219], v[6:9]
	v_mfma_f32_16x16x32_bf16 v[2:5], v[172:175], v[216:219], v[2:5]
	s_barrier
	s_add_i32 s62, s62, 2
	s_add_u32 s60, s60, 0x10000
	s_addc_u32 s61, s61, 0
	s_add_u32 s18, s18, 0x100
	s_addc_u32 s19, s19, 0
	s_cmp_gt_u32 s62, 5
	s_cbranch_scc0 .LBB0_428
	s_and_b64 vcc, exec, s[6:7]
	s_cbranch_vccz .LBB0_431
	s_barrier

; #define PG8_STAGE(bufoff, gbase, voff) do { _Pragma("unroll") for (int _i = 0; _i < 2; ++_i) \
;         __builtin_amdgcn_global_load_lds((const unsigned*)((const char*)(gbase) + (voff)[_i]), (LAS unsigned*)(lds + (bufoff) + ldsw + _i * 8192), 16, 0, 0); } while (0)
; #define PG8_LDA(dst, b, h) do { _Pragma("unroll") for (int m = 0; m < 4; ++m) _Pragma("unroll") for (int k = 0; k < 2; ++k) dst[m][k] = *(const LAS bf16x8*)(lds + PG8_SA(b, h) + aoff + m * 2048 + k * 1024); } while (0)
; #define PG8_LDB(dst, b, h) do { _Pragma("unroll") for (int n = 0; n < 2; ++n) _Pragma("unroll") for (int k = 0; k < 2; ++k) dst[n][k] = *(const LAS bf16x8*)(lds + PG8_SB(b, h) + boff + n * 2048 + k * 1024); } while (0)
; #define PG8_MMA(ai, bj, At, Bt) do { __builtin_amdgcn_s_setprio(1); _Pragma("unroll") for (int m = 0; m < 4; ++m) _Pragma("unroll") for (int n = 0; n < 2; ++n) _Pragma("unroll") for (int k = 0; k < 2; ++k) \
;         acc[ai][bj][m][n] = __builtin_amdgcn_mfma_f32_16x16x32_bf16(Bt[n][k], At[m][k], acc[ai][bj][m][n], 0, 0, 0); __builtin_amdgcn_s_setprio(0); } while (0)
; #define PG8_WAIT_V(n) asm volatile("s_waitcnt vmcnt(" #n ")" ::: "memory")
; #define PG8_WAIT_L(n) asm volatile("s_waitcnt lgkmcnt(" #n ")" ::: "memory")
; #define PG8_BAR __builtin_amdgcn_s_barrier()
; #define PG8_SCHED __builtin_amdgcn_sched_barrier(0)
; template <class Epi, class Sched>
; __device__ __forceinline__ void gemm_phase(const int tid, LAS unsigned char* lds, const Gemm g, const Sched& S, const Epi& E) {
;     ...
;             const bool last = (t == nt - 2);
;             const char* a1 = cA + (size_t)(t + 1) * kstepA;
;             const char* a2 = last ? nA : cA + (size_t)(t + 2) * kstepA; const char* b2 = last ? nB : cB + (size_t)(t + 2) * kstepB;
;             const char* a3 = a2 + kstepA; const char* b3 = b2 + kstepB;
;             PG8_LDB(B0, 0, 0); PG8_LDB(B1, 0, 1); PG8_SCHED; PG8_LDA(At, 0, 0); PG8_STAGE(PG8_SA(1, 1), a1 + hstepA, voffA);
;             PG8_WAIT_V(8); PG8_WAIT_L(0); PG8_BAR; PG8_MMA(0, 0, At, B0); PG8_MMA(0, 1, At, B1); PG8_BAR; PG8_SCHED;
;             PG8_LDA(At, 0, 1); PG8_STAGE(PG8_SB(0, 0), b2, voffB); PG8_STAGE(PG8_SB(0, 1), b2 + hstepB, voffB); PG8_STAGE(PG8_SA(0, 0), a2, voffA);
;             PG8_WAIT_V(8); PG8_WAIT_L(0); PG8_BAR; PG8_MMA(1, 0, At, B0); PG8_MMA(1, 1, At, B1); PG8_BAR; PG8_SCHED;
.LBB0_887:
	s_add_u32 s20, s18, 0xfffc0080
	s_addc_u32 s21, s19, -1
	s_add_i32 s36, 16, 0x10000
	s_cmp_eq_u32 s65, 12
	s_cselect_b32 s23, s9, s21
	s_cselect_b32 s22, s61, s20
	v_add_u32_e32 v0, s36, v236
	s_cselect_b32 s21, s11, s64
	s_cselect_b32 s20, s62, s63
	s_add_i32 s37, 16, 0x14000
	ds_read_b128 v[130:133], v0
	ds_read_b128 v[134:137], v0 offset:1024
	ds_read_b128 v[138:141], v0 offset:2048
	ds_read_b128 v[142:145], v0 offset:3072
	v_add_u32_e32 v0, s37, v236
	ds_read_b128 v[146:149], v0
	ds_read_b128 v[150:153], v0 offset:1024
	ds_read_b128 v[154:157], v0 offset:2048
	ds_read_b128 v[158:161], v0 offset:3072
	s_add_i32 m0, s34, 0xc000
	ds_read_b128 v[162:165], v237
	ds_read_b128 v[166:169], v237 offset:1024
	ds_read_b128 v[170:173], v237 offset:2048
	ds_read_b128 v[174:177], v237 offset:3072
	ds_read_b128 v[178:181], v237 offset:4096
	ds_read_b128 v[182:185], v237 offset:5120
	ds_read_b128 v[186:189], v237 offset:6144
	ds_read_b128 v[190:193], v237 offset:7168
	global_load_lds_dwordx4 v218, s[18:19]
	s_add_i32 m0, s34, 0xe000
	s_nop 0
	global_load_lds_dwordx4 v216, s[18:19]
	s_waitcnt vmcnt(8)
	s_waitcnt lgkmcnt(0)
	s_barrier
	s_waitcnt lgkmcnt(0)
	v_mfma_f32_16x16x32_bf16 v[126:129], v[130:133], v[162:165], v[126:129]
	v_mfma_f32_16x16x32_bf16 v[122:125], v[138:141], v[162:165], v[122:125]
	v_mfma_f32_16x16x32_bf16 v[110:113], v[130:133], v[170:173], v[110:113]
	v_mfma_f32_16x16x32_bf16 v[106:109], v[138:141], v[170:173], v[106:109]
	v_mfma_f32_16x16x32_bf16 v[98:101], v[130:133], v[178:181], v[98:101]
	v_mfma_f32_16x16x32_bf16 v[90:93], v[138:141], v[178:181], v[90:93]
	v_mfma_f32_16x16x32_bf16 v[78:81], v[130:133], v[186:189], v[78:81]
	v_mfma_f32_16x16x32_bf16 v[74:77], v[138:141], v[186:189], v[74:77]
	v_mfma_f32_16x16x32_bf16 v[126:129], v[134:137], v[166:169], v[126:129]
	v_mfma_f32_16x16x32_bf16 v[122:125], v[142:145], v[166:169], v[122:125]
	v_mfma_f32_16x16x32_bf16 v[110:113], v[134:137], v[174:177], v[110:113]
	v_mfma_f32_16x16x32_bf16 v[106:109], v[142:145], v[174:177], v[106:109]
	v_mfma_f32_16x16x32_bf16 v[98:101], v[134:137], v[182:185], v[98:101]
	v_mfma_f32_16x16x32_bf16 v[90:93], v[142:145], v[182:185], v[90:93]
	v_mfma_f32_16x16x32_bf16 v[78:81], v[134:137], v[190:193], v[78:81]
	v_mfma_f32_16x16x32_bf16 v[74:77], v[142:145], v[190:193], v[74:77]
	v_mfma_f32_16x16x32_bf16 v[118:121], v[146:149], v[162:165], v[118:121]
	v_mfma_f32_16x16x32_bf16 v[114:117], v[154:157], v[162:165], v[114:117]
	v_mfma_f32_16x16x32_bf16 v[102:105], v[146:149], v[170:173], v[102:105]
	v_mfma_f32_16x16x32_bf16 v[94:97], v[154:157], v[170:173], v[94:97]
	v_mfma_f32_16x16x32_bf16 v[86:89], v[146:149], v[178:181], v[86:89]
	v_mfma_f32_16x16x32_bf16 v[82:85], v[154:157], v[178:181], v[82:85]
	v_mfma_f32_16x16x32_bf16 v[70:73], v[146:149], v[186:189], v[70:73]
	v_mfma_f32_16x16x32_bf16 v[66:69], v[154:157], v[186:189], v[66:69]
	v_mfma_f32_16x16x32_bf16 v[118:121], v[150:153], v[166:169], v[118:121]
	v_mfma_f32_16x16x32_bf16 v[114:117], v[158:161], v[166:169], v[114:117]
	v_mfma_f32_16x16x32_bf16 v[102:105], v[150:153], v[174:177], v[102:105]
	v_mfma_f32_16x16x32_bf16 v[94:97], v[158:161], v[174:177], v[94:97]
	v_mfma_f32_16x16x32_bf16 v[86:89], v[150:153], v[182:185], v[86:89]
	v_mfma_f32_16x16x32_bf16 v[82:85], v[158:161], v[182:185], v[82:85]
	v_mfma_f32_16x16x32_bf16 v[70:73], v[150:153], v[190:193], v[70:73]
	v_mfma_f32_16x16x32_bf16 v[66:69], v[158:161], v[190:193], v[66:69]
	s_barrier
	s_add_i32 s36, s36, s31
	s_mov_b32 m0, s36
	ds_read_b128 v[162:165], v237 offset:16384
	ds_read_b128 v[166:169], v237 offset:17408
	ds_read_b128 v[170:173], v237 offset:18432
	ds_read_b128 v[174:177], v237 offset:19456
	ds_read_b128 v[178:181], v237 offset:20480
	ds_read_b128 v[182:185], v237 offset:21504
	ds_read_b128 v[186:189], v237 offset:22528
	ds_read_b128 v[190:193], v237 offset:23552
	global_load_lds_dwordx4 v210, s[20:21]
	s_add_i32 m0, s36, 0x2000
	s_add_u32 s66, s20, 0x4000
	s_addc_u32 s67, s21, 0
	s_add_i32 s36, s37, s31
	global_load_lds_dwordx4 v214, s[20:21]
	s_mov_b32 m0, s36
	v_lshl_add_u64 v[206:207], s[22:23], 0, v[212:213]
	global_load_lds_dwordx4 v210, s[66:67]
	s_add_i32 m0, s36, 0x2000
	s_nop 0
	global_load_lds_dwordx4 v214, s[66:67]
	v_lshl_add_u64 v[204:205], s[22:23], 0, v[208:209]
	s_mov_b32 m0, s34
	s_nop 0
	global_load_lds_dwordx4 v[204:205], off
	s_mov_b32 m0, s35
	s_nop 0
	global_load_lds_dwordx4 v[206:207], off
	s_waitcnt vmcnt(8)
	s_waitcnt lgkmcnt(0)
	s_barrier
	s_waitcnt lgkmcnt(0)
	v_mfma_f32_16x16x32_bf16 v[62:65], v[130:133], v[162:165], v[62:65]
	v_mfma_f32_16x16x32_bf16 v[58:61], v[138:141], v[162:165], v[58:61]
	v_mfma_f32_16x16x32_bf16 v[46:49], v[130:133], v[170:173], v[46:49]
	v_mfma_f32_16x16x32_bf16 v[42:45], v[138:141], v[170:173], v[42:45]
	v_mfma_f32_16x16x32_bf16 v[34:37], v[130:133], v[178:181], v[34:37]
	v_mfma_f32_16x16x32_bf16 v[26:29], v[138:141], v[178:181], v[26:29]
	v_mfma_f32_16x16x32_bf16 v[14:17], v[130:133], v[186:189], v[14:17]
	v_mfma_f32_16x16x32_bf16 v[10:13], v[138:141], v[186:189], v[10:13]
	v_mfma_f32_16x16x32_bf16 v[62:65], v[134:137], v[166:169], v[62:65]
	v_mfma_f32_16x16x32_bf16 v[58:61], v[142:145], v[166:169], v[58:61]
	v_mfma_f32_16x16x32_bf16 v[46:49], v[134:137], v[174:177], v[46:49]
	v_mfma_f32_16x16x32_bf16 v[42:45], v[142:145], v[174:177], v[42:45]
	v_mfma_f32_16x16x32_bf16 v[34:37], v[134:137], v[182:185], v[34:37]
	v_mfma_f32_16x16x32_bf16 v[26:29], v[142:145], v[182:185], v[26:29]
	v_mfma_f32_16x16x32_bf16 v[14:17], v[134:137], v[190:193], v[14:17]
	v_mfma_f32_16x16x32_bf16 v[10:13], v[142:145], v[190:193], v[10:13]
	v_mfma_f32_16x16x32_bf16 v[54:57], v[146:149], v[162:165], v[54:57]
	v_mfma_f32_16x16x32_bf16 v[50:53], v[154:157], v[162:165], v[50:53]
	v_mfma_f32_16x16x32_bf16 v[38:41], v[146:149], v[170:173], v[38:41]
	v_mfma_f32_16x16x32_bf16 v[30:33], v[154:157], v[170:173], v[30:33]
	v_mfma_f32_16x16x32_bf16 v[22:25], v[146:149], v[178:181], v[22:25]
	v_mfma_f32_16x16x32_bf16 v[18:21], v[154:157], v[178:181], v[18:21]
	v_mfma_f32_16x16x32_bf16 v[6:9], v[146:149], v[186:189], v[6:9]
	v_mfma_f32_16x16x32_bf16 v[2:5], v[154:157], v[186:189], v[2:5]
	v_mfma_f32_16x16x32_bf16 v[54:57], v[150:153], v[166:169], v[54:57]
	v_mfma_f32_16x16x32_bf16 v[50:53], v[158:161], v[166:169], v[50:53]
	v_mfma_f32_16x16x32_bf16 v[38:41], v[150:153], v[174:177], v[38:41]
	v_mfma_f32_16x16x32_bf16 v[30:33], v[158:161], v[174:177], v[30:33]
	v_mfma_f32_16x16x32_bf16 v[22:25], v[150:153], v[182:185], v[22:25]
	v_mfma_f32_16x16x32_bf16 v[18:21], v[158:161], v[182:185], v[18:21]
	v_mfma_f32_16x16x32_bf16 v[6:9], v[150:153], v[190:193], v[6:9]
	v_mfma_f32_16x16x32_bf16 v[2:5], v[158:161], v[190:193], v[2:5]
	s_barrier
; #define PG8_STAGE(bufoff, gbase, voff) do { _Pragma("unroll") for (int _i = 0; _i < 2; ++_i) \
;         __builtin_amdgcn_global_load_lds((const unsigned*)((const char*)(gbase) + (voff)[_i]), (LAS unsigned*)(lds + (bufoff) + ldsw + _i * 8192), 16, 0, 0); } while (0)
; #define PG8_LDA(dst, b, h) do { _Pragma("unroll") for (int m = 0; m < 4; ++m) _Pragma("unroll") for (int k = 0; k < 2; ++k) dst[m][k] = *(const LAS bf16x8*)(lds + PG8_SA(b, h) + aoff + m * 2048 + k * 1024); } while (0)
; #define PG8_LDB(dst, b, h) do { _Pragma("unroll") for (int n = 0; n < 2; ++n) _Pragma("unroll") for (int k = 0; k < 2; ++k) dst[n][k] = *(const LAS bf16x8*)(lds + PG8_SB(b, h) + boff + n * 2048 + k * 1024); } while (0)
; #define PG8_MMA(ai, bj, At, Bt) do { __builtin_amdgcn_s_setprio(1); _Pragma("unroll") for (int m = 0; m < 4; ++m) _Pragma("unroll") for (int n = 0; n < 2; ++n) _Pragma("unroll") for (int k = 0; k < 2; ++k) \
;         acc[ai][bj][m][n] = __builtin_amdgcn_mfma_f32_16x16x32_bf16(Bt[n][k], At[m][k], acc[ai][bj][m][n], 0, 0, 0); __builtin_amdgcn_s_setprio(0); } while (0)
; #define PG8_WAIT_V(n) asm volatile("s_waitcnt vmcnt(" #n ")" ::: "memory")
; #define PG8_WAIT_L(n) asm volatile("s_waitcnt lgkmcnt(" #n ")" ::: "memory")
; #define PG8_BAR __builtin_amdgcn_s_barrier()
; #define PG8_SCHED __builtin_amdgcn_sched_barrier(0)
; template <class Epi, class Sched>
; __device__ __forceinline__ void gemm_phase(const int tid, LAS unsigned char* lds, const Gemm g, const Sched& S, const Epi& E) {
;     ...
;             PG8_LDB(B0, 1, 0); PG8_LDB(B1, 1, 1); PG8_SCHED; PG8_LDA(At, 1, 0); PG8_STAGE(PG8_SA(0, 1), a2 + hstepA, voffA);
;             PG8_WAIT_V(8); PG8_WAIT_L(0); PG8_BAR; PG8_MMA(0, 0, At, B0); PG8_MMA(0, 1, At, B1); PG8_BAR; PG8_SCHED;
;             PG8_LDA(At, 1, 1); PG8_STAGE(PG8_SB(1, 0), b3, voffB); PG8_STAGE(PG8_SB(1, 1), b3 + hstepB, voffB); PG8_STAGE(PG8_SA(1, 0), a3, voffA);
;             PG8_WAIT_V(8); PG8_WAIT_L(0); PG8_BAR; PG8_MMA(1, 0, At, B0); PG8_MMA(1, 1, At, B1); PG8_BAR; PG8_SCHED;
;         }
;         if (wr == 0) PG8_BAR;
	s_add_i32 s36, 16, 0x18000
	v_add_u32_e32 v0, s36, v236
	s_add_i32 s37, 16, 0x1c000
	ds_read_b128 v[130:133], v0
	ds_read_b128 v[134:137], v0 offset:1024
	ds_read_b128 v[138:141], v0 offset:2048
	ds_read_b128 v[142:145], v0 offset:3072
	v_add_u32_e32 v0, s37, v236
	ds_read_b128 v[146:149], v0
	ds_read_b128 v[150:153], v0 offset:1024
	ds_read_b128 v[154:157], v0 offset:2048
	ds_read_b128 v[158:161], v0 offset:3072
	s_add_u32 s22, s22, 0x40000
	s_addc_u32 s23, s23, 0
	s_mov_b32 m0, s52
	ds_read_b128 v[162:165], v237 offset:32768
	ds_read_b128 v[166:169], v237 offset:33792
	ds_read_b128 v[170:173], v237 offset:34816
	ds_read_b128 v[174:177], v237 offset:35840
	ds_read_b128 v[178:181], v237 offset:36864
	ds_read_b128 v[182:185], v237 offset:37888
	ds_read_b128 v[186:189], v237 offset:38912
	ds_read_b128 v[190:193], v237 offset:39936
	global_load_lds_dwordx4 v208, s[22:23]
	s_mov_b32 m0, s53
	s_nop 0
	global_load_lds_dwordx4 v212, s[22:23]
	s_waitcnt vmcnt(8)
	s_waitcnt lgkmcnt(0)
	s_barrier
	s_waitcnt lgkmcnt(0)
	v_mfma_f32_16x16x32_bf16 v[126:129], v[130:133], v[162:165], v[126:129]
	v_mfma_f32_16x16x32_bf16 v[122:125], v[138:141], v[162:165], v[122:125]
	v_mfma_f32_16x16x32_bf16 v[110:113], v[130:133], v[170:173], v[110:113]
	v_mfma_f32_16x16x32_bf16 v[106:109], v[138:141], v[170:173], v[106:109]
	v_mfma_f32_16x16x32_bf16 v[98:101], v[130:133], v[178:181], v[98:101]
	v_mfma_f32_16x16x32_bf16 v[90:93], v[138:141], v[178:181], v[90:93]
	v_mfma_f32_16x16x32_bf16 v[78:81], v[130:133], v[186:189], v[78:81]
	v_mfma_f32_16x16x32_bf16 v[74:77], v[138:141], v[186:189], v[74:77]
	v_mfma_f32_16x16x32_bf16 v[126:129], v[134:137], v[166:169], v[126:129]
	v_mfma_f32_16x16x32_bf16 v[122:125], v[142:145], v[166:169], v[122:125]
	v_mfma_f32_16x16x32_bf16 v[110:113], v[134:137], v[174:177], v[110:113]
	v_mfma_f32_16x16x32_bf16 v[106:109], v[142:145], v[174:177], v[106:109]
	v_mfma_f32_16x16x32_bf16 v[98:101], v[134:137], v[182:185], v[98:101]
	v_mfma_f32_16x16x32_bf16 v[90:93], v[142:145], v[182:185], v[90:93]
	v_mfma_f32_16x16x32_bf16 v[78:81], v[134:137], v[190:193], v[78:81]
	v_mfma_f32_16x16x32_bf16 v[74:77], v[142:145], v[190:193], v[74:77]
	v_mfma_f32_16x16x32_bf16 v[118:121], v[146:149], v[162:165], v[118:121]
	v_mfma_f32_16x16x32_bf16 v[114:117], v[154:157], v[162:165], v[114:117]
	v_mfma_f32_16x16x32_bf16 v[102:105], v[146:149], v[170:173], v[102:105]
	v_mfma_f32_16x16x32_bf16 v[94:97], v[154:157], v[170:173], v[94:97]
	v_mfma_f32_16x16x32_bf16 v[86:89], v[146:149], v[178:181], v[86:89]
	v_mfma_f32_16x16x32_bf16 v[82:85], v[154:157], v[178:181], v[82:85]
	v_mfma_f32_16x16x32_bf16 v[70:73], v[146:149], v[186:189], v[70:73]
	v_mfma_f32_16x16x32_bf16 v[66:69], v[154:157], v[186:189], v[66:69]
	v_mfma_f32_16x16x32_bf16 v[118:121], v[150:153], v[166:169], v[118:121]
	v_mfma_f32_16x16x32_bf16 v[114:117], v[158:161], v[166:169], v[114:117]
	v_mfma_f32_16x16x32_bf16 v[102:105], v[150:153], v[174:177], v[102:105]
	v_mfma_f32_16x16x32_bf16 v[94:97], v[158:161], v[174:177], v[94:97]
	v_mfma_f32_16x16x32_bf16 v[86:89], v[150:153], v[182:185], v[86:89]
	v_mfma_f32_16x16x32_bf16 v[82:85], v[158:161], v[182:185], v[82:85]
	v_mfma_f32_16x16x32_bf16 v[70:73], v[150:153], v[190:193], v[70:73]
	v_mfma_f32_16x16x32_bf16 v[66:69], v[158:161], v[190:193], v[66:69]
	s_barrier
	s_add_u32 s22, s20, 0x8000
	s_addc_u32 s23, s21, 0
	s_add_i32 s36, s36, s31
	s_mov_b32 m0, s36
	ds_read_b128 v[162:165], v237 offset:49152
	ds_read_b128 v[166:169], v237 offset:50176
	ds_read_b128 v[170:173], v237 offset:51200
	ds_read_b128 v[174:177], v237 offset:52224
	ds_read_b128 v[178:181], v237 offset:53248
	ds_read_b128 v[182:185], v237 offset:54272
	ds_read_b128 v[186:189], v237 offset:55296
	ds_read_b128 v[190:193], v237 offset:56320
	global_load_lds_dwordx4 v210, s[22:23]
	s_add_i32 m0, s36, 0x2000
	s_add_u32 s20, s20, 0xc000
	s_addc_u32 s21, s21, 0
	global_load_lds_dwordx4 v214, s[22:23]
	s_add_i32 s22, s37, s31
	s_mov_b32 m0, s22
	v_lshl_add_u64 v[204:205], v[204:205], 0, s[88:89]
	global_load_lds_dwordx4 v210, s[20:21]
	s_add_i32 m0, s22, 0x2000
	s_nop 0
	global_load_lds_dwordx4 v214, s[20:21]
	s_mov_b32 m0, s58
	s_nop 0
	global_load_lds_dwordx4 v[204:205], off
	v_lshl_add_u64 v[204:205], v[206:207], 0, s[88:89]
	s_mov_b32 m0, s59
	s_nop 0
	global_load_lds_dwordx4 v[204:205], off
	s_waitcnt vmcnt(8)
	s_waitcnt lgkmcnt(0)
	s_barrier
	s_waitcnt lgkmcnt(0)
	v_mfma_f32_16x16x32_bf16 v[62:65], v[130:133], v[162:165], v[62:65]
	v_mfma_f32_16x16x32_bf16 v[58:61], v[138:141], v[162:165], v[58:61]
	v_mfma_f32_16x16x32_bf16 v[46:49], v[130:133], v[170:173], v[46:49]
	v_mfma_f32_16x16x32_bf16 v[42:45], v[138:141], v[170:173], v[42:45]
	v_mfma_f32_16x16x32_bf16 v[34:37], v[130:133], v[178:181], v[34:37]
	v_mfma_f32_16x16x32_bf16 v[26:29], v[138:141], v[178:181], v[26:29]
	v_mfma_f32_16x16x32_bf16 v[14:17], v[130:133], v[186:189], v[14:17]
	v_mfma_f32_16x16x32_bf16 v[10:13], v[138:141], v[186:189], v[10:13]
	v_mfma_f32_16x16x32_bf16 v[62:65], v[134:137], v[166:169], v[62:65]
	v_mfma_f32_16x16x32_bf16 v[58:61], v[142:145], v[166:169], v[58:61]
	v_mfma_f32_16x16x32_bf16 v[46:49], v[134:137], v[174:177], v[46:49]
	v_mfma_f32_16x16x32_bf16 v[42:45], v[142:145], v[174:177], v[42:45]
	v_mfma_f32_16x16x32_bf16 v[34:37], v[134:137], v[182:185], v[34:37]
	v_mfma_f32_16x16x32_bf16 v[26:29], v[142:145], v[182:185], v[26:29]
	v_mfma_f32_16x16x32_bf16 v[14:17], v[134:137], v[190:193], v[14:17]
	v_mfma_f32_16x16x32_bf16 v[10:13], v[142:145], v[190:193], v[10:13]
	v_mfma_f32_16x16x32_bf16 v[54:57], v[146:149], v[162:165], v[54:57]
	v_mfma_f32_16x16x32_bf16 v[50:53], v[154:157], v[162:165], v[50:53]
	v_mfma_f32_16x16x32_bf16 v[38:41], v[146:149], v[170:173], v[38:41]
	v_mfma_f32_16x16x32_bf16 v[30:33], v[154:157], v[170:173], v[30:33]
	v_mfma_f32_16x16x32_bf16 v[22:25], v[146:149], v[178:181], v[22:25]
	v_mfma_f32_16x16x32_bf16 v[18:21], v[154:157], v[178:181], v[18:21]
	v_mfma_f32_16x16x32_bf16 v[6:9], v[146:149], v[186:189], v[6:9]
	v_mfma_f32_16x16x32_bf16 v[2:5], v[154:157], v[186:189], v[2:5]
	v_mfma_f32_16x16x32_bf16 v[54:57], v[150:153], v[166:169], v[54:57]
	v_mfma_f32_16x16x32_bf16 v[50:53], v[158:161], v[166:169], v[50:53]
	v_mfma_f32_16x16x32_bf16 v[38:41], v[150:153], v[174:177], v[38:41]
	v_mfma_f32_16x16x32_bf16 v[30:33], v[158:161], v[174:177], v[30:33]
	v_mfma_f32_16x16x32_bf16 v[22:25], v[150:153], v[182:185], v[22:25]
	v_mfma_f32_16x16x32_bf16 v[18:21], v[158:161], v[182:185], v[18:21]
	v_mfma_f32_16x16x32_bf16 v[6:9], v[150:153], v[190:193], v[6:9]
	v_mfma_f32_16x16x32_bf16 v[2:5], v[158:161], v[190:193], v[2:5]
	s_barrier
	s_add_i32 s65, s65, 2
	s_add_u32 s63, s63, 0x10000
	s_addc_u32 s64, s64, 0
	s_add_u32 s18, s18, 0x100
	s_addc_u32 s19, s19, 0
	s_cmp_gt_u32 s65, 13
	s_cbranch_scc0 .LBB0_887
	s_and_b64 vcc, exec, s[6:7]
	s_cbranch_vccz .LBB0_890
	s_barrier

; #define PG8_STAGE(bufoff, gbase, voff) do { _Pragma("unroll") for (int _i = 0; _i < 2; ++_i) \
;         __builtin_amdgcn_global_load_lds((const unsigned*)((const char*)(gbase) + (voff)[_i]), (LAS unsigned*)(lds + (bufoff) + ldsw + _i * 8192), 16, 0, 0); } while (0)
; #define PG8_LDA(dst, b, h) do { _Pragma("unroll") for (int m = 0; m < 4; ++m) _Pragma("unroll") for (int k = 0; k < 2; ++k) dst[m][k] = *(const LAS bf16x8*)(lds + PG8_SA(b, h) + aoff + m * 2048 + k * 1024); } while (0)
; #define PG8_LDB(dst, b, h) do { _Pragma("unroll") for (int n = 0; n < 2; ++n) _Pragma("unroll") for (int k = 0; k < 2; ++k) dst[n][k] = *(const LAS bf16x8*)(lds + PG8_SB(b, h) + boff + n * 2048 + k * 1024); } while (0)
; #define PG8_MMA(ai, bj, At, Bt) do { __builtin_amdgcn_s_setprio(1); _Pragma("unroll") for (int m = 0; m < 4; ++m) _Pragma("unroll") for (int n = 0; n < 2; ++n) _Pragma("unroll") for (int k = 0; k < 2; ++k) \
;         acc[ai][bj][m][n] = __builtin_amdgcn_mfma_f32_16x16x32_bf16(Bt[n][k], At[m][k], acc[ai][bj][m][n], 0, 0, 0); __builtin_amdgcn_s_setprio(0); } while (0)
; #define PG8_WAIT_V(n) asm volatile("s_waitcnt vmcnt(" #n ")" ::: "memory")
; #define PG8_WAIT_L(n) asm volatile("s_waitcnt lgkmcnt(" #n ")" ::: "memory")
; #define PG8_BAR __builtin_amdgcn_s_barrier()
; #define PG8_SCHED __builtin_amdgcn_sched_barrier(0)
; template <class Epi, class Sched>
; __device__ __forceinline__ void gemm_phase(const int tid, LAS unsigned char* lds, const Gemm g, const Sched& S, const Epi& E) {
;     ...
;             const bool last = (t == nt - 2);
;             const char* a1 = cA + (size_t)(t + 1) * kstepA;
;             const char* a2 = last ? nA : cA + (size_t)(t + 2) * kstepA; const char* b2 = last ? nB : cB + (size_t)(t + 2) * kstepB;
;             const char* a3 = a2 + kstepA; const char* b3 = b2 + kstepB;
;             PG8_LDB(B0, 0, 0); PG8_LDB(B1, 0, 1); PG8_SCHED; PG8_LDA(At, 0, 0); PG8_STAGE(PG8_SA(1, 1), a1 + hstepA, voffA);
;             PG8_WAIT_V(8); PG8_WAIT_L(0); PG8_BAR; PG8_MMA(0, 0, At, B0); PG8_MMA(0, 1, At, B1); PG8_BAR; PG8_SCHED;
;             PG8_LDA(At, 0, 1); PG8_STAGE(PG8_SB(0, 0), b2, voffB); PG8_STAGE(PG8_SB(0, 1), b2 + hstepB, voffB); PG8_STAGE(PG8_SA(0, 0), a2, voffA);
;             PG8_WAIT_V(8); PG8_WAIT_L(0); PG8_BAR; PG8_MMA(1, 0, At, B0); PG8_MMA(1, 1, At, B1); PG8_BAR; PG8_SCHED;
.LBB0_962:
	s_add_u32 s18, s16, 0x4000
	s_addc_u32 s19, s17, 0
	s_cmp_eq_u32 s62, 28
	s_cselect_b32 s22, s58, s18
	s_cselect_b32 s23, s9, s19
	s_cselect_b32 s20, s59, s60
	s_cselect_b32 s21, s7, s61
	s_add_u32 s18, s22, 0x8000
	s_addc_u32 s19, s23, 0
	s_add_i32 s36, 16, 0x10000
	s_add_i32 s37, 16, 0x14000
	v_add_u32_e32 v148, s36, v157
	v_add_u32_e32 v168, s37, v157
	ds_read_b128 v[130:133], v148
	ds_read_b128 v[134:137], v148 offset:1024
	ds_read_b128 v[138:141], v148 offset:2048
	ds_read_b128 v[148:151], v148 offset:3072
	ds_read_b128 v[152:155], v168
	ds_read_b128 v[160:163], v168 offset:1024
	ds_read_b128 v[164:167], v168 offset:2048
	ds_read_b128 v[168:171], v168 offset:3072
	s_add_i32 m0, s34, 0xc000
	ds_read_b128 v[172:175], v159
	ds_read_b128 v[176:179], v159 offset:1024
	ds_read_b128 v[180:183], v159 offset:2048
	ds_read_b128 v[184:187], v159 offset:3072
	ds_read_b128 v[188:191], v159 offset:4096
	ds_read_b128 v[204:207], v159 offset:5120
	ds_read_b128 v[208:211], v159 offset:6144
	ds_read_b128 v[212:215], v159 offset:7168
	global_load_lds_dwordx4 v146, s[16:17]
	s_add_i32 m0, s34, 0xe000
	s_nop 0
	global_load_lds_dwordx4 v144, s[16:17]
	s_waitcnt vmcnt(8)
	s_waitcnt lgkmcnt(0)
	s_barrier
	s_waitcnt lgkmcnt(0)
	v_mfma_f32_16x16x32_bf16 v[126:129], v[130:133], v[172:175], v[126:129]
	v_mfma_f32_16x16x32_bf16 v[122:125], v[138:141], v[172:175], v[122:125]
	v_mfma_f32_16x16x32_bf16 v[118:121], v[130:133], v[180:183], v[118:121]
	v_mfma_f32_16x16x32_bf16 v[106:109], v[138:141], v[180:183], v[106:109]
	v_mfma_f32_16x16x32_bf16 v[102:105], v[130:133], v[188:191], v[102:105]
	v_mfma_f32_16x16x32_bf16 v[90:93], v[138:141], v[188:191], v[90:93]
	v_mfma_f32_16x16x32_bf16 v[86:89], v[130:133], v[208:211], v[86:89]
	v_mfma_f32_16x16x32_bf16 v[74:77], v[138:141], v[208:211], v[74:77]
	v_mfma_f32_16x16x32_bf16 v[126:129], v[134:137], v[176:179], v[126:129]
	v_mfma_f32_16x16x32_bf16 v[122:125], v[148:151], v[176:179], v[122:125]
	v_mfma_f32_16x16x32_bf16 v[118:121], v[134:137], v[184:187], v[118:121]
	v_mfma_f32_16x16x32_bf16 v[106:109], v[148:151], v[184:187], v[106:109]
	v_mfma_f32_16x16x32_bf16 v[102:105], v[134:137], v[204:207], v[102:105]
	v_mfma_f32_16x16x32_bf16 v[90:93], v[148:151], v[204:207], v[90:93]
	v_mfma_f32_16x16x32_bf16 v[86:89], v[134:137], v[212:215], v[86:89]
	v_mfma_f32_16x16x32_bf16 v[74:77], v[148:151], v[212:215], v[74:77]
	v_mfma_f32_16x16x32_bf16 v[114:117], v[152:155], v[172:175], v[114:117]
	v_mfma_f32_16x16x32_bf16 v[110:113], v[164:167], v[172:175], v[110:113]
	v_mfma_f32_16x16x32_bf16 v[98:101], v[152:155], v[180:183], v[98:101]
	v_mfma_f32_16x16x32_bf16 v[94:97], v[164:167], v[180:183], v[94:97]
	v_mfma_f32_16x16x32_bf16 v[82:85], v[152:155], v[188:191], v[82:85]
	v_mfma_f32_16x16x32_bf16 v[78:81], v[164:167], v[188:191], v[78:81]
	v_mfma_f32_16x16x32_bf16 v[70:73], v[152:155], v[208:211], v[70:73]
	v_mfma_f32_16x16x32_bf16 v[66:69], v[164:167], v[208:211], v[66:69]
	v_mfma_f32_16x16x32_bf16 v[114:117], v[160:163], v[176:179], v[114:117]
	v_mfma_f32_16x16x32_bf16 v[110:113], v[168:171], v[176:179], v[110:113]
	v_mfma_f32_16x16x32_bf16 v[98:101], v[160:163], v[184:187], v[98:101]
	v_mfma_f32_16x16x32_bf16 v[94:97], v[168:171], v[184:187], v[94:97]
	v_mfma_f32_16x16x32_bf16 v[82:85], v[160:163], v[204:207], v[82:85]
	v_mfma_f32_16x16x32_bf16 v[78:81], v[168:171], v[204:207], v[78:81]
	v_mfma_f32_16x16x32_bf16 v[70:73], v[160:163], v[212:215], v[70:73]
	v_mfma_f32_16x16x32_bf16 v[66:69], v[168:171], v[212:215], v[66:69]
	s_barrier
	s_add_i32 s36, s36, s31
	s_mov_b32 m0, s36
	ds_read_b128 v[172:175], v159 offset:16384
	ds_read_b128 v[176:179], v159 offset:17408
	ds_read_b128 v[180:183], v159 offset:18432
	ds_read_b128 v[184:187], v159 offset:19456
	ds_read_b128 v[188:191], v159 offset:20480
	ds_read_b128 v[204:207], v159 offset:21504
	ds_read_b128 v[208:211], v159 offset:22528
	ds_read_b128 v[212:215], v159 offset:23552
	global_load_lds_dwordx4 v0, s[20:21]
	s_add_i32 m0, s36, 0x2000
	s_add_u32 s64, s20, 0x4000
	s_addc_u32 s65, s21, 0
	s_add_i32 s36, s37, s31
	global_load_lds_dwordx4 v142, s[20:21]
	s_mov_b32 m0, s36
	s_nop 0
	global_load_lds_dwordx4 v0, s[64:65]
	s_add_i32 m0, s36, 0x2000
	s_nop 0
	global_load_lds_dwordx4 v142, s[64:65]
	s_mov_b32 m0, s34
	s_nop 0
	global_load_lds_dwordx4 v0, s[22:23]
	s_mov_b32 m0, s35
	s_nop 0
	global_load_lds_dwordx4 v142, s[22:23]
	s_waitcnt vmcnt(8)
	s_waitcnt lgkmcnt(0)
	s_barrier
	s_waitcnt lgkmcnt(0)
	v_mfma_f32_16x16x32_bf16 v[62:65], v[130:133], v[172:175], v[62:65]
	v_mfma_f32_16x16x32_bf16 v[58:61], v[138:141], v[172:175], v[58:61]
	v_mfma_f32_16x16x32_bf16 v[54:57], v[130:133], v[180:183], v[54:57]
	v_mfma_f32_16x16x32_bf16 v[42:45], v[138:141], v[180:183], v[42:45]
	v_mfma_f32_16x16x32_bf16 v[38:41], v[130:133], v[188:191], v[38:41]
	v_mfma_f32_16x16x32_bf16 v[26:29], v[138:141], v[188:191], v[26:29]
	v_mfma_f32_16x16x32_bf16 v[22:25], v[130:133], v[208:211], v[22:25]
	v_mfma_f32_16x16x32_bf16 v[10:13], v[138:141], v[208:211], v[10:13]
	v_mfma_f32_16x16x32_bf16 v[62:65], v[134:137], v[176:179], v[62:65]
	v_mfma_f32_16x16x32_bf16 v[58:61], v[148:151], v[176:179], v[58:61]
	v_mfma_f32_16x16x32_bf16 v[54:57], v[134:137], v[184:187], v[54:57]
	v_mfma_f32_16x16x32_bf16 v[42:45], v[148:151], v[184:187], v[42:45]
	v_mfma_f32_16x16x32_bf16 v[38:41], v[134:137], v[204:207], v[38:41]
	v_mfma_f32_16x16x32_bf16 v[26:29], v[148:151], v[204:207], v[26:29]
	v_mfma_f32_16x16x32_bf16 v[22:25], v[134:137], v[212:215], v[22:25]
	v_mfma_f32_16x16x32_bf16 v[10:13], v[148:151], v[212:215], v[10:13]
	v_mfma_f32_16x16x32_bf16 v[50:53], v[152:155], v[172:175], v[50:53]
	v_mfma_f32_16x16x32_bf16 v[46:49], v[164:167], v[172:175], v[46:49]
	v_mfma_f32_16x16x32_bf16 v[34:37], v[152:155], v[180:183], v[34:37]
	v_mfma_f32_16x16x32_bf16 v[30:33], v[164:167], v[180:183], v[30:33]
	v_mfma_f32_16x16x32_bf16 v[18:21], v[152:155], v[188:191], v[18:21]
	v_mfma_f32_16x16x32_bf16 v[14:17], v[164:167], v[188:191], v[14:17]
	v_mfma_f32_16x16x32_bf16 v[6:9], v[152:155], v[208:211], v[6:9]
	v_mfma_f32_16x16x32_bf16 v[2:5], v[164:167], v[208:211], v[2:5]
	v_mfma_f32_16x16x32_bf16 v[50:53], v[160:163], v[176:179], v[50:53]
	v_mfma_f32_16x16x32_bf16 v[46:49], v[168:171], v[176:179], v[46:49]
	v_mfma_f32_16x16x32_bf16 v[34:37], v[160:163], v[184:187], v[34:37]
	v_mfma_f32_16x16x32_bf16 v[30:33], v[168:171], v[184:187], v[30:33]
	v_mfma_f32_16x16x32_bf16 v[18:21], v[160:163], v[204:207], v[18:21]
	v_mfma_f32_16x16x32_bf16 v[14:17], v[168:171], v[204:207], v[14:17]
	v_mfma_f32_16x16x32_bf16 v[6:9], v[160:163], v[212:215], v[6:9]
	v_mfma_f32_16x16x32_bf16 v[2:5], v[168:171], v[212:215], v[2:5]
	s_barrier
; #define PG8_STAGE(bufoff, gbase, voff) do { _Pragma("unroll") for (int _i = 0; _i < 2; ++_i) \
;         __builtin_amdgcn_global_load_lds((const unsigned*)((const char*)(gbase) + (voff)[_i]), (LAS unsigned*)(lds + (bufoff) + ldsw + _i * 8192), 16, 0, 0); } while (0)
; #define PG8_LDA(dst, b, h) do { _Pragma("unroll") for (int m = 0; m < 4; ++m) _Pragma("unroll") for (int k = 0; k < 2; ++k) dst[m][k] = *(const LAS bf16x8*)(lds + PG8_SA(b, h) + aoff + m * 2048 + k * 1024); } while (0)
; #define PG8_LDB(dst, b, h) do { _Pragma("unroll") for (int n = 0; n < 2; ++n) _Pragma("unroll") for (int k = 0; k < 2; ++k) dst[n][k] = *(const LAS bf16x8*)(lds + PG8_SB(b, h) + boff + n * 2048 + k * 1024); } while (0)
; #define PG8_MMA(ai, bj, At, Bt) do { __builtin_amdgcn_s_setprio(1); _Pragma("unroll") for (int m = 0; m < 4; ++m) _Pragma("unroll") for (int n = 0; n < 2; ++n) _Pragma("unroll") for (int k = 0; k < 2; ++k) \
;         acc[ai][bj][m][n] = __builtin_amdgcn_mfma_f32_16x16x32_bf16(Bt[n][k], At[m][k], acc[ai][bj][m][n], 0, 0, 0); __builtin_amdgcn_s_setprio(0); } while (0)
; #define PG8_WAIT_V(n) asm volatile("s_waitcnt vmcnt(" #n ")" ::: "memory")
; #define PG8_WAIT_L(n) asm volatile("s_waitcnt lgkmcnt(" #n ")" ::: "memory")
; #define PG8_BAR __builtin_amdgcn_s_barrier()
; #define PG8_SCHED __builtin_amdgcn_sched_barrier(0)
; template <class Epi, class Sched>
; __device__ __forceinline__ void gemm_phase(const int tid, LAS unsigned char* lds, const Gemm g, const Sched& S, const Epi& E) {
;     ...
;             PG8_LDB(B0, 1, 0); PG8_LDB(B1, 1, 1); PG8_SCHED; PG8_LDA(At, 1, 0); PG8_STAGE(PG8_SA(0, 1), a2 + hstepA, voffA);
;             PG8_WAIT_V(8); PG8_WAIT_L(0); PG8_BAR; PG8_MMA(0, 0, At, B0); PG8_MMA(0, 1, At, B1); PG8_BAR; PG8_SCHED;
;             PG8_LDA(At, 1, 1); PG8_STAGE(PG8_SB(1, 0), b3, voffB); PG8_STAGE(PG8_SB(1, 1), b3 + hstepB, voffB); PG8_STAGE(PG8_SA(1, 0), a3, voffA);
;             PG8_WAIT_V(8); PG8_WAIT_L(0); PG8_BAR; PG8_MMA(1, 0, At, B0); PG8_MMA(1, 1, At, B1); PG8_BAR; PG8_SCHED;
;         }
;         if (wr == 0) PG8_BAR;
	s_add_i32 s36, 16, 0x18000
	s_add_i32 s37, 16, 0x1c000
	v_add_u32_e32 v148, s36, v157
	v_add_u32_e32 v168, s37, v157
	ds_read_b128 v[130:133], v148
	ds_read_b128 v[134:137], v148 offset:1024
	ds_read_b128 v[138:141], v148 offset:2048
	ds_read_b128 v[148:151], v148 offset:3072
	ds_read_b128 v[152:155], v168
	ds_read_b128 v[160:163], v168 offset:1024
	ds_read_b128 v[164:167], v168 offset:2048
	ds_read_b128 v[168:171], v168 offset:3072
	s_add_u32 s22, s22, 0x4000
	s_addc_u32 s23, s23, 0
	s_mov_b32 m0, s52
	ds_read_b128 v[172:175], v159 offset:32768
	ds_read_b128 v[176:179], v159 offset:33792
	ds_read_b128 v[180:183], v159 offset:34816
	ds_read_b128 v[184:187], v159 offset:35840
	ds_read_b128 v[188:191], v159 offset:36864
	ds_read_b128 v[204:207], v159 offset:37888
	ds_read_b128 v[208:211], v159 offset:38912
	ds_read_b128 v[212:215], v159 offset:39936
	global_load_lds_dwordx4 v0, s[22:23]
	s_mov_b32 m0, s53
	s_nop 0
	global_load_lds_dwordx4 v142, s[22:23]
	s_waitcnt vmcnt(8)
	s_waitcnt lgkmcnt(0)
	s_barrier
	s_waitcnt lgkmcnt(0)
	v_mfma_f32_16x16x32_bf16 v[126:129], v[130:133], v[172:175], v[126:129]
	v_mfma_f32_16x16x32_bf16 v[122:125], v[138:141], v[172:175], v[122:125]
	v_mfma_f32_16x16x32_bf16 v[118:121], v[130:133], v[180:183], v[118:121]
	v_mfma_f32_16x16x32_bf16 v[106:109], v[138:141], v[180:183], v[106:109]
	v_mfma_f32_16x16x32_bf16 v[102:105], v[130:133], v[188:191], v[102:105]
	v_mfma_f32_16x16x32_bf16 v[90:93], v[138:141], v[188:191], v[90:93]
	v_mfma_f32_16x16x32_bf16 v[86:89], v[130:133], v[208:211], v[86:89]
	v_mfma_f32_16x16x32_bf16 v[74:77], v[138:141], v[208:211], v[74:77]
	v_mfma_f32_16x16x32_bf16 v[126:129], v[134:137], v[176:179], v[126:129]
	v_mfma_f32_16x16x32_bf16 v[122:125], v[148:151], v[176:179], v[122:125]
	v_mfma_f32_16x16x32_bf16 v[118:121], v[134:137], v[184:187], v[118:121]
	v_mfma_f32_16x16x32_bf16 v[106:109], v[148:151], v[184:187], v[106:109]
	v_mfma_f32_16x16x32_bf16 v[102:105], v[134:137], v[204:207], v[102:105]
	v_mfma_f32_16x16x32_bf16 v[90:93], v[148:151], v[204:207], v[90:93]
	v_mfma_f32_16x16x32_bf16 v[86:89], v[134:137], v[212:215], v[86:89]
	v_mfma_f32_16x16x32_bf16 v[74:77], v[148:151], v[212:215], v[74:77]
	v_mfma_f32_16x16x32_bf16 v[114:117], v[152:155], v[172:175], v[114:117]
	v_mfma_f32_16x16x32_bf16 v[110:113], v[164:167], v[172:175], v[110:113]
	v_mfma_f32_16x16x32_bf16 v[98:101], v[152:155], v[180:183], v[98:101]
	v_mfma_f32_16x16x32_bf16 v[94:97], v[164:167], v[180:183], v[94:97]
	v_mfma_f32_16x16x32_bf16 v[82:85], v[152:155], v[188:191], v[82:85]
	v_mfma_f32_16x16x32_bf16 v[78:81], v[164:167], v[188:191], v[78:81]
	v_mfma_f32_16x16x32_bf16 v[70:73], v[152:155], v[208:211], v[70:73]
	v_mfma_f32_16x16x32_bf16 v[66:69], v[164:167], v[208:211], v[66:69]
	v_mfma_f32_16x16x32_bf16 v[114:117], v[160:163], v[176:179], v[114:117]
	v_mfma_f32_16x16x32_bf16 v[110:113], v[168:171], v[176:179], v[110:113]
	v_mfma_f32_16x16x32_bf16 v[98:101], v[160:163], v[184:187], v[98:101]
	v_mfma_f32_16x16x32_bf16 v[94:97], v[168:171], v[184:187], v[94:97]
	v_mfma_f32_16x16x32_bf16 v[82:85], v[160:163], v[204:207], v[82:85]
	v_mfma_f32_16x16x32_bf16 v[78:81], v[168:171], v[204:207], v[78:81]
	v_mfma_f32_16x16x32_bf16 v[70:73], v[160:163], v[212:215], v[70:73]
	v_mfma_f32_16x16x32_bf16 v[66:69], v[168:171], v[212:215], v[66:69]
	s_barrier
	s_add_u32 s22, s20, 0x8000
	s_addc_u32 s23, s21, 0
	s_add_i32 s36, s36, s31
	s_mov_b32 m0, s36
	ds_read_b128 v[172:175], v159 offset:49152
	ds_read_b128 v[176:179], v159 offset:50176
	ds_read_b128 v[180:183], v159 offset:51200
	ds_read_b128 v[184:187], v159 offset:52224
	ds_read_b128 v[188:191], v159 offset:53248
	ds_read_b128 v[204:207], v159 offset:54272
	ds_read_b128 v[208:211], v159 offset:55296
	ds_read_b128 v[212:215], v159 offset:56320
	global_load_lds_dwordx4 v0, s[22:23]
	s_add_i32 m0, s36, 0x2000
	s_add_u32 s20, s20, 0xc000
	s_addc_u32 s21, s21, 0
	global_load_lds_dwordx4 v142, s[22:23]
	s_add_i32 s22, s37, s31
	s_mov_b32 m0, s22
	s_nop 0
	global_load_lds_dwordx4 v0, s[20:21]
	s_add_i32 m0, s22, 0x2000
	s_nop 0
	global_load_lds_dwordx4 v142, s[20:21]
	s_mov_b32 m0, s54
	s_nop 0
	global_load_lds_dwordx4 v0, s[18:19]
	s_mov_b32 m0, s55
	s_nop 0
	global_load_lds_dwordx4 v142, s[18:19]
	s_waitcnt vmcnt(8)
	s_waitcnt lgkmcnt(0)
	s_barrier
	s_waitcnt lgkmcnt(0)
	v_mfma_f32_16x16x32_bf16 v[62:65], v[130:133], v[172:175], v[62:65]
	v_mfma_f32_16x16x32_bf16 v[58:61], v[138:141], v[172:175], v[58:61]
	v_mfma_f32_16x16x32_bf16 v[54:57], v[130:133], v[180:183], v[54:57]
	v_mfma_f32_16x16x32_bf16 v[42:45], v[138:141], v[180:183], v[42:45]
	v_mfma_f32_16x16x32_bf16 v[38:41], v[130:133], v[188:191], v[38:41]
	v_mfma_f32_16x16x32_bf16 v[26:29], v[138:141], v[188:191], v[26:29]
	v_mfma_f32_16x16x32_bf16 v[22:25], v[130:133], v[208:211], v[22:25]
	v_mfma_f32_16x16x32_bf16 v[10:13], v[138:141], v[208:211], v[10:13]
	v_mfma_f32_16x16x32_bf16 v[62:65], v[134:137], v[176:179], v[62:65]
	v_mfma_f32_16x16x32_bf16 v[58:61], v[148:151], v[176:179], v[58:61]
	v_mfma_f32_16x16x32_bf16 v[54:57], v[134:137], v[184:187], v[54:57]
	v_mfma_f32_16x16x32_bf16 v[42:45], v[148:151], v[184:187], v[42:45]
	v_mfma_f32_16x16x32_bf16 v[38:41], v[134:137], v[204:207], v[38:41]
	v_mfma_f32_16x16x32_bf16 v[26:29], v[148:151], v[204:207], v[26:29]
	v_mfma_f32_16x16x32_bf16 v[22:25], v[134:137], v[212:215], v[22:25]
	v_mfma_f32_16x16x32_bf16 v[10:13], v[148:151], v[212:215], v[10:13]
	v_mfma_f32_16x16x32_bf16 v[50:53], v[152:155], v[172:175], v[50:53]
	v_mfma_f32_16x16x32_bf16 v[46:49], v[164:167], v[172:175], v[46:49]
	v_mfma_f32_16x16x32_bf16 v[34:37], v[152:155], v[180:183], v[34:37]
	v_mfma_f32_16x16x32_bf16 v[30:33], v[164:167], v[180:183], v[30:33]
	v_mfma_f32_16x16x32_bf16 v[18:21], v[152:155], v[188:191], v[18:21]
	v_mfma_f32_16x16x32_bf16 v[14:17], v[164:167], v[188:191], v[14:17]
	v_mfma_f32_16x16x32_bf16 v[6:9], v[152:155], v[208:211], v[6:9]
	v_mfma_f32_16x16x32_bf16 v[2:5], v[164:167], v[208:211], v[2:5]
	v_mfma_f32_16x16x32_bf16 v[50:53], v[160:163], v[176:179], v[50:53]
	v_mfma_f32_16x16x32_bf16 v[46:49], v[168:171], v[176:179], v[46:49]
	v_mfma_f32_16x16x32_bf16 v[34:37], v[160:163], v[184:187], v[34:37]
	v_mfma_f32_16x16x32_bf16 v[30:33], v[168:171], v[184:187], v[30:33]
	v_mfma_f32_16x16x32_bf16 v[18:21], v[160:163], v[204:207], v[18:21]
	v_mfma_f32_16x16x32_bf16 v[14:17], v[168:171], v[204:207], v[14:17]
	v_mfma_f32_16x16x32_bf16 v[6:9], v[160:163], v[212:215], v[6:9]
	v_mfma_f32_16x16x32_bf16 v[2:5], v[168:171], v[212:215], v[2:5]
	s_barrier
	s_add_i32 s62, s62, 2
	s_add_u32 s60, s60, 0x10000
	s_addc_u32 s61, s61, 0
	s_add_u32 s16, s16, 0x10000
	s_addc_u32 s17, s17, 0
	s_cmp_gt_u32 s62, 29
	s_cbranch_scc0 .LBB0_962
	s_and_b64 vcc, exec, s[2:3]
	s_cbranch_vccz .LBB0_965
	s_barrier

; #define PG8_STAGE(bufoff, gbase, voff) do { _Pragma("unroll") for (int _i = 0; _i < 2; ++_i) \
;         __builtin_amdgcn_global_load_lds((const unsigned*)((const char*)(gbase) + (voff)[_i]), (LAS unsigned*)(lds + (bufoff) + ldsw + _i * 8192), 16, 0, 0); } while (0)
; #define PG8_LDA(dst, b, h) do { _Pragma("unroll") for (int m = 0; m < 4; ++m) _Pragma("unroll") for (int k = 0; k < 2; ++k) dst[m][k] = *(const LAS bf16x8*)(lds + PG8_SA(b, h) + aoff + m * 2048 + k * 1024); } while (0)
; #define PG8_LDB(dst, b, h) do { _Pragma("unroll") for (int n = 0; n < 2; ++n) _Pragma("unroll") for (int k = 0; k < 2; ++k) dst[n][k] = *(const LAS bf16x8*)(lds + PG8_SB(b, h) + boff + n * 2048 + k * 1024); } while (0)
; #define PG8_MMA(ai, bj, At, Bt) do { __builtin_amdgcn_s_setprio(1); _Pragma("unroll") for (int m = 0; m < 4; ++m) _Pragma("unroll") for (int n = 0; n < 2; ++n) _Pragma("unroll") for (int k = 0; k < 2; ++k) \
;         acc[ai][bj][m][n] = __builtin_amdgcn_mfma_f32_16x16x32_bf16(Bt[n][k], At[m][k], acc[ai][bj][m][n], 0, 0, 0); __builtin_amdgcn_s_setprio(0); } while (0)
; #define PG8_WAIT_V(n) asm volatile("s_waitcnt vmcnt(" #n ")" ::: "memory")
; #define PG8_WAIT_L(n) asm volatile("s_waitcnt lgkmcnt(" #n ")" ::: "memory")
; #define PG8_BAR __builtin_amdgcn_s_barrier()
; #define PG8_SCHED __builtin_amdgcn_sched_barrier(0)
; template <class Epi, class Sched>
; __device__ __forceinline__ void gemm_phase(const int tid, LAS unsigned char* lds, const Gemm g, const Sched& S, const Epi& E) {
;     ...
;             const bool last = (t == nt - 2);
;             const char* a1 = cA + (size_t)(t + 1) * kstepA;
;             const char* a2 = last ? nA : cA + (size_t)(t + 2) * kstepA; const char* b2 = last ? nB : cB + (size_t)(t + 2) * kstepB;
;             const char* a3 = a2 + kstepA; const char* b3 = b2 + kstepB;
;             PG8_LDB(B0, 0, 0); PG8_LDB(B1, 0, 1); PG8_SCHED; PG8_LDA(At, 0, 0); PG8_STAGE(PG8_SA(1, 1), a1 + hstepA, voffA);
;             PG8_WAIT_V(8); PG8_WAIT_L(0); PG8_BAR; PG8_MMA(0, 0, At, B0); PG8_MMA(0, 1, At, B1); PG8_BAR; PG8_SCHED;
;             PG8_LDA(At, 0, 1); PG8_STAGE(PG8_SB(0, 0), b2, voffB); PG8_STAGE(PG8_SB(0, 1), b2 + hstepB, voffB); PG8_STAGE(PG8_SA(0, 0), a2, voffA);
;             PG8_WAIT_V(8); PG8_WAIT_L(0); PG8_BAR; PG8_MMA(1, 0, At, B0); PG8_MMA(1, 1, At, B1); PG8_BAR; PG8_SCHED;
.LBB0_1100:
	s_add_u32 s22, s20, 0x4000
	s_addc_u32 s23, s21, 0
	s_cmp_eq_u32 s76, 28
	s_cselect_b32 s26, s64, s22
	s_cselect_b32 s27, s13, s23
	s_cselect_b32 s24, s65, s66
	s_cselect_b32 s25, s11, s67
	s_add_u32 s22, s26, 0x8000
	s_addc_u32 s23, s27, 0
	s_add_i32 s36, 16, 0x10000
	v_add_u32_e32 v0, s36, v145
	s_add_i32 s37, 16, 0x14000
	ds_read_b128 v[148:151], v0
	ds_read_b128 v[152:155], v0 offset:1024
	ds_read_b128 v[156:159], v0 offset:2048
	ds_read_b128 v[160:163], v0 offset:3072
	v_add_u32_e32 v0, s37, v145
	ds_read_b128 v[164:167], v0
	ds_read_b128 v[168:171], v0 offset:1024
	ds_read_b128 v[172:175], v0 offset:2048
	ds_read_b128 v[176:179], v0 offset:3072
	s_add_i32 m0, s19, 0xc000
	ds_read_b128 v[180:183], v146
	ds_read_b128 v[184:187], v146 offset:1024
	ds_read_b128 v[188:191], v146 offset:2048
	ds_read_b128 v[204:207], v146 offset:3072
	ds_read_b128 v[208:211], v146 offset:4096
	ds_read_b128 v[212:215], v146 offset:5120
	ds_read_b128 v[216:219], v146 offset:6144
	ds_read_b128 v[220:223], v146 offset:7168
	global_load_lds_dwordx4 v140, s[20:21]
	s_add_i32 m0, s19, 0xe000
	s_nop 0
	global_load_lds_dwordx4 v138, s[20:21]
	s_waitcnt vmcnt(8)
	s_waitcnt lgkmcnt(0)
	s_barrier
	s_waitcnt lgkmcnt(0)
	v_mfma_f32_16x16x32_bf16 v[126:129], v[148:151], v[180:183], v[126:129]
	v_mfma_f32_16x16x32_bf16 v[122:125], v[156:159], v[180:183], v[122:125]
	v_mfma_f32_16x16x32_bf16 v[110:113], v[148:151], v[188:191], v[110:113]
	v_mfma_f32_16x16x32_bf16 v[106:109], v[156:159], v[188:191], v[106:109]
	v_mfma_f32_16x16x32_bf16 v[94:97], v[148:151], v[208:211], v[94:97]
	v_mfma_f32_16x16x32_bf16 v[90:93], v[156:159], v[208:211], v[90:93]
	v_mfma_f32_16x16x32_bf16 v[78:81], v[148:151], v[216:219], v[78:81]
	v_mfma_f32_16x16x32_bf16 v[74:77], v[156:159], v[216:219], v[74:77]
	v_mfma_f32_16x16x32_bf16 v[126:129], v[152:155], v[184:187], v[126:129]
	v_mfma_f32_16x16x32_bf16 v[122:125], v[160:163], v[184:187], v[122:125]
	v_mfma_f32_16x16x32_bf16 v[110:113], v[152:155], v[204:207], v[110:113]
	v_mfma_f32_16x16x32_bf16 v[106:109], v[160:163], v[204:207], v[106:109]
	v_mfma_f32_16x16x32_bf16 v[94:97], v[152:155], v[212:215], v[94:97]
	v_mfma_f32_16x16x32_bf16 v[90:93], v[160:163], v[212:215], v[90:93]
	v_mfma_f32_16x16x32_bf16 v[78:81], v[152:155], v[220:223], v[78:81]
	v_mfma_f32_16x16x32_bf16 v[74:77], v[160:163], v[220:223], v[74:77]
	v_mfma_f32_16x16x32_bf16 v[118:121], v[164:167], v[180:183], v[118:121]
	v_mfma_f32_16x16x32_bf16 v[114:117], v[172:175], v[180:183], v[114:117]
	v_mfma_f32_16x16x32_bf16 v[102:105], v[164:167], v[188:191], v[102:105]
	v_mfma_f32_16x16x32_bf16 v[98:101], v[172:175], v[188:191], v[98:101]
	v_mfma_f32_16x16x32_bf16 v[86:89], v[164:167], v[208:211], v[86:89]
	v_mfma_f32_16x16x32_bf16 v[82:85], v[172:175], v[208:211], v[82:85]
	v_mfma_f32_16x16x32_bf16 v[70:73], v[164:167], v[216:219], v[70:73]
	v_mfma_f32_16x16x32_bf16 v[66:69], v[172:175], v[216:219], v[66:69]
	v_mfma_f32_16x16x32_bf16 v[118:121], v[168:171], v[184:187], v[118:121]
	v_mfma_f32_16x16x32_bf16 v[114:117], v[176:179], v[184:187], v[114:117]
	v_mfma_f32_16x16x32_bf16 v[102:105], v[168:171], v[204:207], v[102:105]
	v_mfma_f32_16x16x32_bf16 v[98:101], v[176:179], v[204:207], v[98:101]
	v_mfma_f32_16x16x32_bf16 v[86:89], v[168:171], v[212:215], v[86:89]
	v_mfma_f32_16x16x32_bf16 v[82:85], v[176:179], v[212:215], v[82:85]
	v_mfma_f32_16x16x32_bf16 v[70:73], v[168:171], v[220:223], v[70:73]
	v_mfma_f32_16x16x32_bf16 v[66:69], v[176:179], v[220:223], v[66:69]
	s_barrier
	s_add_i32 s36, s36, s52
	s_mov_b32 m0, s36
	ds_read_b128 v[180:183], v146 offset:16384
	ds_read_b128 v[184:187], v146 offset:17408
	ds_read_b128 v[188:191], v146 offset:18432
	ds_read_b128 v[204:207], v146 offset:19456
	ds_read_b128 v[208:211], v146 offset:20480
	ds_read_b128 v[212:215], v146 offset:21504
	ds_read_b128 v[216:219], v146 offset:22528
	ds_read_b128 v[220:223], v146 offset:23552
	global_load_lds_dwordx4 v134, s[24:25]
	s_add_i32 m0, s36, 0x2000
	s_add_u32 s78, s24, 0x4000
	s_addc_u32 s79, s25, 0
	s_add_i32 s36, s37, s52
	global_load_lds_dwordx4 v130, s[24:25]
	s_mov_b32 m0, s36
	s_nop 0
	global_load_lds_dwordx4 v134, s[78:79]
	s_add_i32 m0, s36, 0x2000
	s_nop 0
	global_load_lds_dwordx4 v130, s[78:79]
	s_mov_b32 m0, s19
	s_nop 0
	global_load_lds_dwordx4 v136, s[26:27]
	s_mov_b32 m0, s54
	s_nop 0
	global_load_lds_dwordx4 v132, s[26:27]
	s_waitcnt vmcnt(8)
	s_waitcnt lgkmcnt(0)
	s_barrier
	s_waitcnt lgkmcnt(0)
	v_mfma_f32_16x16x32_bf16 v[62:65], v[148:151], v[180:183], v[62:65]
	v_mfma_f32_16x16x32_bf16 v[58:61], v[156:159], v[180:183], v[58:61]
	v_mfma_f32_16x16x32_bf16 v[46:49], v[148:151], v[188:191], v[46:49]
	v_mfma_f32_16x16x32_bf16 v[42:45], v[156:159], v[188:191], v[42:45]
	v_mfma_f32_16x16x32_bf16 v[30:33], v[148:151], v[208:211], v[30:33]
	v_mfma_f32_16x16x32_bf16 v[26:29], v[156:159], v[208:211], v[26:29]
	v_mfma_f32_16x16x32_bf16 v[14:17], v[148:151], v[216:219], v[14:17]
	v_mfma_f32_16x16x32_bf16 v[10:13], v[156:159], v[216:219], v[10:13]
	v_mfma_f32_16x16x32_bf16 v[62:65], v[152:155], v[184:187], v[62:65]
	v_mfma_f32_16x16x32_bf16 v[58:61], v[160:163], v[184:187], v[58:61]
	v_mfma_f32_16x16x32_bf16 v[46:49], v[152:155], v[204:207], v[46:49]
	v_mfma_f32_16x16x32_bf16 v[42:45], v[160:163], v[204:207], v[42:45]
	v_mfma_f32_16x16x32_bf16 v[30:33], v[152:155], v[212:215], v[30:33]
	v_mfma_f32_16x16x32_bf16 v[26:29], v[160:163], v[212:215], v[26:29]
	v_mfma_f32_16x16x32_bf16 v[14:17], v[152:155], v[220:223], v[14:17]
	v_mfma_f32_16x16x32_bf16 v[10:13], v[160:163], v[220:223], v[10:13]
	v_mfma_f32_16x16x32_bf16 v[54:57], v[164:167], v[180:183], v[54:57]
	v_mfma_f32_16x16x32_bf16 v[50:53], v[172:175], v[180:183], v[50:53]
	v_mfma_f32_16x16x32_bf16 v[38:41], v[164:167], v[188:191], v[38:41]
	v_mfma_f32_16x16x32_bf16 v[34:37], v[172:175], v[188:191], v[34:37]
	v_mfma_f32_16x16x32_bf16 v[22:25], v[164:167], v[208:211], v[22:25]
	v_mfma_f32_16x16x32_bf16 v[18:21], v[172:175], v[208:211], v[18:21]
	v_mfma_f32_16x16x32_bf16 v[6:9], v[164:167], v[216:219], v[6:9]
	v_mfma_f32_16x16x32_bf16 v[2:5], v[172:175], v[216:219], v[2:5]
	v_mfma_f32_16x16x32_bf16 v[54:57], v[168:171], v[184:187], v[54:57]
	v_mfma_f32_16x16x32_bf16 v[50:53], v[176:179], v[184:187], v[50:53]
	v_mfma_f32_16x16x32_bf16 v[38:41], v[168:171], v[204:207], v[38:41]
	v_mfma_f32_16x16x32_bf16 v[34:37], v[176:179], v[204:207], v[34:37]
	v_mfma_f32_16x16x32_bf16 v[22:25], v[168:171], v[212:215], v[22:25]
	v_mfma_f32_16x16x32_bf16 v[18:21], v[176:179], v[212:215], v[18:21]
	v_mfma_f32_16x16x32_bf16 v[6:9], v[168:171], v[220:223], v[6:9]
	v_mfma_f32_16x16x32_bf16 v[2:5], v[176:179], v[220:223], v[2:5]
	s_barrier
; #define PG8_STAGE(bufoff, gbase, voff) do { _Pragma("unroll") for (int _i = 0; _i < 2; ++_i) \
;         __builtin_amdgcn_global_load_lds((const unsigned*)((const char*)(gbase) + (voff)[_i]), (LAS unsigned*)(lds + (bufoff) + ldsw + _i * 8192), 16, 0, 0); } while (0)
; #define PG8_LDA(dst, b, h) do { _Pragma("unroll") for (int m = 0; m < 4; ++m) _Pragma("unroll") for (int k = 0; k < 2; ++k) dst[m][k] = *(const LAS bf16x8*)(lds + PG8_SA(b, h) + aoff + m * 2048 + k * 1024); } while (0)
; #define PG8_LDB(dst, b, h) do { _Pragma("unroll") for (int n = 0; n < 2; ++n) _Pragma("unroll") for (int k = 0; k < 2; ++k) dst[n][k] = *(const LAS bf16x8*)(lds + PG8_SB(b, h) + boff + n * 2048 + k * 1024); } while (0)
; #define PG8_MMA(ai, bj, At, Bt) do { __builtin_amdgcn_s_setprio(1); _Pragma("unroll") for (int m = 0; m < 4; ++m) _Pragma("unroll") for (int n = 0; n < 2; ++n) _Pragma("unroll") for (int k = 0; k < 2; ++k) \
;         acc[ai][bj][m][n] = __builtin_amdgcn_mfma_f32_16x16x32_bf16(Bt[n][k], At[m][k], acc[ai][bj][m][n], 0, 0, 0); __builtin_amdgcn_s_setprio(0); } while (0)
; #define PG8_WAIT_V(n) asm volatile("s_waitcnt vmcnt(" #n ")" ::: "memory")
; #define PG8_WAIT_L(n) asm volatile("s_waitcnt lgkmcnt(" #n ")" ::: "memory")
; #define PG8_BAR __builtin_amdgcn_s_barrier()
; #define PG8_SCHED __builtin_amdgcn_sched_barrier(0)
; template <class Epi, class Sched>
; __device__ __forceinline__ void gemm_phase(const int tid, LAS unsigned char* lds, const Gemm g, const Sched& S, const Epi& E) {
;     ...
;             PG8_LDB(B0, 1, 0); PG8_LDB(B1, 1, 1); PG8_SCHED; PG8_LDA(At, 1, 0); PG8_STAGE(PG8_SA(0, 1), a2 + hstepA, voffA);
;             PG8_WAIT_V(8); PG8_WAIT_L(0); PG8_BAR; PG8_MMA(0, 0, At, B0); PG8_MMA(0, 1, At, B1); PG8_BAR; PG8_SCHED;
;             PG8_LDA(At, 1, 1); PG8_STAGE(PG8_SB(1, 0), b3, voffB); PG8_STAGE(PG8_SB(1, 1), b3 + hstepB, voffB); PG8_STAGE(PG8_SA(1, 0), a3, voffA);
;             PG8_WAIT_V(8); PG8_WAIT_L(0); PG8_BAR; PG8_MMA(1, 0, At, B0); PG8_MMA(1, 1, At, B1); PG8_BAR; PG8_SCHED;
;         }
;         if (wr == 0) PG8_BAR;
	s_add_i32 s36, 16, 0x18000
	v_add_u32_e32 v0, s36, v145
	s_add_i32 s37, 16, 0x1c000
	ds_read_b128 v[148:151], v0
	ds_read_b128 v[152:155], v0 offset:1024
	ds_read_b128 v[156:159], v0 offset:2048
	ds_read_b128 v[160:163], v0 offset:3072
	v_add_u32_e32 v0, s37, v145
	ds_read_b128 v[164:167], v0
	ds_read_b128 v[168:171], v0 offset:1024
	ds_read_b128 v[172:175], v0 offset:2048
	ds_read_b128 v[176:179], v0 offset:3072
	s_add_u32 s26, s26, 0x4000
	s_addc_u32 s27, s27, 0
	s_mov_b32 m0, s55
	ds_read_b128 v[180:183], v146 offset:32768
	ds_read_b128 v[184:187], v146 offset:33792
	ds_read_b128 v[188:191], v146 offset:34816
	ds_read_b128 v[204:207], v146 offset:35840
	ds_read_b128 v[208:211], v146 offset:36864
	ds_read_b128 v[212:215], v146 offset:37888
	ds_read_b128 v[216:219], v146 offset:38912
	ds_read_b128 v[220:223], v146 offset:39936
	global_load_lds_dwordx4 v136, s[26:27]
	s_mov_b32 m0, s56
	s_nop 0
	global_load_lds_dwordx4 v132, s[26:27]
	s_waitcnt vmcnt(8)
	s_waitcnt lgkmcnt(0)
	s_barrier
	s_waitcnt lgkmcnt(0)
	v_mfma_f32_16x16x32_bf16 v[126:129], v[148:151], v[180:183], v[126:129]
	v_mfma_f32_16x16x32_bf16 v[122:125], v[156:159], v[180:183], v[122:125]
	v_mfma_f32_16x16x32_bf16 v[110:113], v[148:151], v[188:191], v[110:113]
	v_mfma_f32_16x16x32_bf16 v[106:109], v[156:159], v[188:191], v[106:109]
	v_mfma_f32_16x16x32_bf16 v[94:97], v[148:151], v[208:211], v[94:97]
	v_mfma_f32_16x16x32_bf16 v[90:93], v[156:159], v[208:211], v[90:93]
	v_mfma_f32_16x16x32_bf16 v[78:81], v[148:151], v[216:219], v[78:81]
	v_mfma_f32_16x16x32_bf16 v[74:77], v[156:159], v[216:219], v[74:77]
	v_mfma_f32_16x16x32_bf16 v[126:129], v[152:155], v[184:187], v[126:129]
	v_mfma_f32_16x16x32_bf16 v[122:125], v[160:163], v[184:187], v[122:125]
	v_mfma_f32_16x16x32_bf16 v[110:113], v[152:155], v[204:207], v[110:113]
	v_mfma_f32_16x16x32_bf16 v[106:109], v[160:163], v[204:207], v[106:109]
	v_mfma_f32_16x16x32_bf16 v[94:97], v[152:155], v[212:215], v[94:97]
	v_mfma_f32_16x16x32_bf16 v[90:93], v[160:163], v[212:215], v[90:93]
	v_mfma_f32_16x16x32_bf16 v[78:81], v[152:155], v[220:223], v[78:81]
	v_mfma_f32_16x16x32_bf16 v[74:77], v[160:163], v[220:223], v[74:77]
	v_mfma_f32_16x16x32_bf16 v[118:121], v[164:167], v[180:183], v[118:121]
	v_mfma_f32_16x16x32_bf16 v[114:117], v[172:175], v[180:183], v[114:117]
	v_mfma_f32_16x16x32_bf16 v[102:105], v[164:167], v[188:191], v[102:105]
	v_mfma_f32_16x16x32_bf16 v[98:101], v[172:175], v[188:191], v[98:101]
	v_mfma_f32_16x16x32_bf16 v[86:89], v[164:167], v[208:211], v[86:89]
	v_mfma_f32_16x16x32_bf16 v[82:85], v[172:175], v[208:211], v[82:85]
	v_mfma_f32_16x16x32_bf16 v[70:73], v[164:167], v[216:219], v[70:73]
	v_mfma_f32_16x16x32_bf16 v[66:69], v[172:175], v[216:219], v[66:69]
	v_mfma_f32_16x16x32_bf16 v[118:121], v[168:171], v[184:187], v[118:121]
	v_mfma_f32_16x16x32_bf16 v[114:117], v[176:179], v[184:187], v[114:117]
	v_mfma_f32_16x16x32_bf16 v[102:105], v[168:171], v[204:207], v[102:105]
	v_mfma_f32_16x16x32_bf16 v[98:101], v[176:179], v[204:207], v[98:101]
	v_mfma_f32_16x16x32_bf16 v[86:89], v[168:171], v[212:215], v[86:89]
	v_mfma_f32_16x16x32_bf16 v[82:85], v[176:179], v[212:215], v[82:85]
	v_mfma_f32_16x16x32_bf16 v[70:73], v[168:171], v[220:223], v[70:73]
	v_mfma_f32_16x16x32_bf16 v[66:69], v[176:179], v[220:223], v[66:69]
	s_barrier
	s_add_u32 s26, s24, 0x8000
	s_addc_u32 s27, s25, 0
	s_add_i32 s36, s36, s52
	s_mov_b32 m0, s36
	ds_read_b128 v[180:183], v146 offset:49152
	ds_read_b128 v[184:187], v146 offset:50176
	ds_read_b128 v[188:191], v146 offset:51200
	ds_read_b128 v[204:207], v146 offset:52224
	ds_read_b128 v[208:211], v146 offset:53248
	ds_read_b128 v[212:215], v146 offset:54272
	ds_read_b128 v[216:219], v146 offset:55296
	ds_read_b128 v[220:223], v146 offset:56320
	global_load_lds_dwordx4 v134, s[26:27]
	s_add_i32 m0, s36, 0x2000
	s_add_u32 s24, s24, 0xc000
	s_addc_u32 s25, s25, 0
	global_load_lds_dwordx4 v130, s[26:27]
	s_add_i32 s26, s37, s52
	s_mov_b32 m0, s26
	s_nop 0
	global_load_lds_dwordx4 v134, s[24:25]
	s_add_i32 m0, s26, 0x2000
	s_nop 0
	global_load_lds_dwordx4 v130, s[24:25]
	s_mov_b32 m0, s59
	s_nop 0
	global_load_lds_dwordx4 v136, s[22:23]
	s_mov_b32 m0, s60
	s_nop 0
	global_load_lds_dwordx4 v132, s[22:23]
	s_waitcnt vmcnt(8)
	s_waitcnt lgkmcnt(0)
	s_barrier
	s_waitcnt lgkmcnt(0)
	v_mfma_f32_16x16x32_bf16 v[62:65], v[148:151], v[180:183], v[62:65]
	v_mfma_f32_16x16x32_bf16 v[58:61], v[156:159], v[180:183], v[58:61]
	v_mfma_f32_16x16x32_bf16 v[46:49], v[148:151], v[188:191], v[46:49]
	v_mfma_f32_16x16x32_bf16 v[42:45], v[156:159], v[188:191], v[42:45]
	v_mfma_f32_16x16x32_bf16 v[30:33], v[148:151], v[208:211], v[30:33]
	v_mfma_f32_16x16x32_bf16 v[26:29], v[156:159], v[208:211], v[26:29]
	v_mfma_f32_16x16x32_bf16 v[14:17], v[148:151], v[216:219], v[14:17]
	v_mfma_f32_16x16x32_bf16 v[10:13], v[156:159], v[216:219], v[10:13]
	v_mfma_f32_16x16x32_bf16 v[62:65], v[152:155], v[184:187], v[62:65]
	v_mfma_f32_16x16x32_bf16 v[58:61], v[160:163], v[184:187], v[58:61]
	v_mfma_f32_16x16x32_bf16 v[46:49], v[152:155], v[204:207], v[46:49]
	v_mfma_f32_16x16x32_bf16 v[42:45], v[160:163], v[204:207], v[42:45]
	v_mfma_f32_16x16x32_bf16 v[30:33], v[152:155], v[212:215], v[30:33]
	v_mfma_f32_16x16x32_bf16 v[26:29], v[160:163], v[212:215], v[26:29]
	v_mfma_f32_16x16x32_bf16 v[14:17], v[152:155], v[220:223], v[14:17]
	v_mfma_f32_16x16x32_bf16 v[10:13], v[160:163], v[220:223], v[10:13]
	v_mfma_f32_16x16x32_bf16 v[54:57], v[164:167], v[180:183], v[54:57]
	v_mfma_f32_16x16x32_bf16 v[50:53], v[172:175], v[180:183], v[50:53]
	v_mfma_f32_16x16x32_bf16 v[38:41], v[164:167], v[188:191], v[38:41]
	v_mfma_f32_16x16x32_bf16 v[34:37], v[172:175], v[188:191], v[34:37]
	v_mfma_f32_16x16x32_bf16 v[22:25], v[164:167], v[208:211], v[22:25]
	v_mfma_f32_16x16x32_bf16 v[18:21], v[172:175], v[208:211], v[18:21]
	v_mfma_f32_16x16x32_bf16 v[6:9], v[164:167], v[216:219], v[6:9]
	v_mfma_f32_16x16x32_bf16 v[2:5], v[172:175], v[216:219], v[2:5]
	v_mfma_f32_16x16x32_bf16 v[54:57], v[168:171], v[184:187], v[54:57]
	v_mfma_f32_16x16x32_bf16 v[50:53], v[176:179], v[184:187], v[50:53]
	v_mfma_f32_16x16x32_bf16 v[38:41], v[168:171], v[204:207], v[38:41]
	v_mfma_f32_16x16x32_bf16 v[34:37], v[176:179], v[204:207], v[34:37]
	v_mfma_f32_16x16x32_bf16 v[22:25], v[168:171], v[212:215], v[22:25]
	v_mfma_f32_16x16x32_bf16 v[18:21], v[176:179], v[212:215], v[18:21]
	v_mfma_f32_16x16x32_bf16 v[6:9], v[168:171], v[220:223], v[6:9]
	v_mfma_f32_16x16x32_bf16 v[2:5], v[176:179], v[220:223], v[2:5]
	s_barrier
	s_add_i32 s76, s76, 2
	s_add_u32 s66, s66, 0x10000
	s_addc_u32 s67, s67, 0
	s_add_u32 s20, s20, 0x10000
	s_addc_u32 s21, s21, 0
	s_cmp_gt_u32 s76, 29
	s_cbranch_scc0 .LBB0_1100
	s_and_b64 vcc, exec, s[6:7]
	s_cbranch_vccz .LBB0_1103
	s_barrier

; #define PG8_STAGE(bufoff, gbase, voff) do { _Pragma("unroll") for (int _i = 0; _i < 2; ++_i) \
;         __builtin_amdgcn_global_load_lds((const unsigned*)((const char*)(gbase) + (voff)[_i]), (LAS unsigned*)(lds + (bufoff) + ldsw + _i * 8192), 16, 0, 0); } while (0)
; #define PG8_LDA(dst, b, h) do { _Pragma("unroll") for (int m = 0; m < 4; ++m) _Pragma("unroll") for (int k = 0; k < 2; ++k) dst[m][k] = *(const LAS bf16x8*)(lds + PG8_SA(b, h) + aoff + m * 2048 + k * 1024); } while (0)
; #define PG8_LDB(dst, b, h) do { _Pragma("unroll") for (int n = 0; n < 2; ++n) _Pragma("unroll") for (int k = 0; k < 2; ++k) dst[n][k] = *(const LAS bf16x8*)(lds + PG8_SB(b, h) + boff + n * 2048 + k * 1024); } while (0)
; #define PG8_MMA(ai, bj, At, Bt) do { __builtin_amdgcn_s_setprio(1); _Pragma("unroll") for (int m = 0; m < 4; ++m) _Pragma("unroll") for (int n = 0; n < 2; ++n) _Pragma("unroll") for (int k = 0; k < 2; ++k) \
;         acc[ai][bj][m][n] = __builtin_amdgcn_mfma_f32_16x16x32_bf16(Bt[n][k], At[m][k], acc[ai][bj][m][n], 0, 0, 0); __builtin_amdgcn_s_setprio(0); } while (0)
; #define PG8_WAIT_V(n) asm volatile("s_waitcnt vmcnt(" #n ")" ::: "memory")
; #define PG8_WAIT_L(n) asm volatile("s_waitcnt lgkmcnt(" #n ")" ::: "memory")
; #define PG8_BAR __builtin_amdgcn_s_barrier()
; #define PG8_SCHED __builtin_amdgcn_sched_barrier(0)
; template <class Epi, class Sched>
; __device__ __forceinline__ void gemm_phase(const int tid, LAS unsigned char* lds, const Gemm g, const Sched& S, const Epi& E) {
;     ...
;             const bool last = (t == nt - 2);
;             const char* a1 = cA + (size_t)(t + 1) * kstepA;
;             const char* a2 = last ? nA : cA + (size_t)(t + 2) * kstepA; const char* b2 = last ? nB : cB + (size_t)(t + 2) * kstepB;
;             const char* a3 = a2 + kstepA; const char* b3 = b2 + kstepB;
;             PG8_LDB(B0, 0, 0); PG8_LDB(B1, 0, 1); PG8_SCHED; PG8_LDA(At, 0, 0); PG8_STAGE(PG8_SA(1, 1), a1 + hstepA, voffA);
;             PG8_WAIT_V(8); PG8_WAIT_L(0); PG8_BAR; PG8_MMA(0, 0, At, B0); PG8_MMA(0, 1, At, B1); PG8_BAR; PG8_SCHED;
;             PG8_LDA(At, 0, 1); PG8_STAGE(PG8_SB(0, 0), b2, voffB); PG8_STAGE(PG8_SB(0, 1), b2 + hstepB, voffB); PG8_STAGE(PG8_SA(0, 0), a2, voffA);
;             PG8_WAIT_V(8); PG8_WAIT_L(0); PG8_BAR; PG8_MMA(1, 0, At, B0); PG8_MMA(1, 1, At, B1); PG8_BAR; PG8_SCHED;
.LBB0_1171:
	s_add_u32 s16, s14, 0x4000
	s_addc_u32 s17, s15, 0
	s_cmpk_eq_i32 s62, 0x54
	s_cselect_b32 s20, s6, s16
	s_cselect_b32 s21, s7, s17
	s_cselect_b32 s18, s12, s60
	s_cselect_b32 s19, s13, s61
	s_add_u32 s16, s20, 0x8000
	s_addc_u32 s17, s21, 0
	s_add_i32 s36, 16, 0x10000
	s_add_i32 s37, 16, 0x14000
	v_add_u32_e32 v148, s36, v157
	v_add_u32_e32 v168, s37, v157
	ds_read_b128 v[130:133], v148
	ds_read_b128 v[134:137], v148 offset:1024
	ds_read_b128 v[138:141], v148 offset:2048
	ds_read_b128 v[148:151], v148 offset:3072
	ds_read_b128 v[152:155], v168
	ds_read_b128 v[160:163], v168 offset:1024
	ds_read_b128 v[164:167], v168 offset:2048
	ds_read_b128 v[168:171], v168 offset:3072
	s_add_i32 m0, s30, 0xc000
	ds_read_b128 v[172:175], v159
	ds_read_b128 v[176:179], v159 offset:1024
	ds_read_b128 v[180:183], v159 offset:2048
	ds_read_b128 v[184:187], v159 offset:3072
	ds_read_b128 v[188:191], v159 offset:4096
	ds_read_b128 v[204:207], v159 offset:5120
	ds_read_b128 v[208:211], v159 offset:6144
	ds_read_b128 v[212:215], v159 offset:7168
	global_load_lds_dwordx4 v146, s[14:15]
	s_add_i32 m0, s30, 0xe000
	s_nop 0
	global_load_lds_dwordx4 v144, s[14:15]
	s_waitcnt vmcnt(8)
	s_waitcnt lgkmcnt(0)
	s_barrier
	s_waitcnt lgkmcnt(0)
	v_mfma_f32_16x16x32_bf16 v[126:129], v[130:133], v[172:175], v[126:129]
	v_mfma_f32_16x16x32_bf16 v[122:125], v[138:141], v[172:175], v[122:125]
	v_mfma_f32_16x16x32_bf16 v[118:121], v[130:133], v[180:183], v[118:121]
	v_mfma_f32_16x16x32_bf16 v[106:109], v[138:141], v[180:183], v[106:109]
	v_mfma_f32_16x16x32_bf16 v[102:105], v[130:133], v[188:191], v[102:105]
	v_mfma_f32_16x16x32_bf16 v[90:93], v[138:141], v[188:191], v[90:93]
	v_mfma_f32_16x16x32_bf16 v[86:89], v[130:133], v[208:211], v[86:89]
	v_mfma_f32_16x16x32_bf16 v[74:77], v[138:141], v[208:211], v[74:77]
	v_mfma_f32_16x16x32_bf16 v[126:129], v[134:137], v[176:179], v[126:129]
	v_mfma_f32_16x16x32_bf16 v[122:125], v[148:151], v[176:179], v[122:125]
	v_mfma_f32_16x16x32_bf16 v[118:121], v[134:137], v[184:187], v[118:121]
	v_mfma_f32_16x16x32_bf16 v[106:109], v[148:151], v[184:187], v[106:109]
	v_mfma_f32_16x16x32_bf16 v[102:105], v[134:137], v[204:207], v[102:105]
	v_mfma_f32_16x16x32_bf16 v[90:93], v[148:151], v[204:207], v[90:93]
	v_mfma_f32_16x16x32_bf16 v[86:89], v[134:137], v[212:215], v[86:89]
	v_mfma_f32_16x16x32_bf16 v[74:77], v[148:151], v[212:215], v[74:77]
	v_mfma_f32_16x16x32_bf16 v[114:117], v[152:155], v[172:175], v[114:117]
	v_mfma_f32_16x16x32_bf16 v[110:113], v[164:167], v[172:175], v[110:113]
	v_mfma_f32_16x16x32_bf16 v[98:101], v[152:155], v[180:183], v[98:101]
	v_mfma_f32_16x16x32_bf16 v[94:97], v[164:167], v[180:183], v[94:97]
	v_mfma_f32_16x16x32_bf16 v[82:85], v[152:155], v[188:191], v[82:85]
	v_mfma_f32_16x16x32_bf16 v[78:81], v[164:167], v[188:191], v[78:81]
	v_mfma_f32_16x16x32_bf16 v[70:73], v[152:155], v[208:211], v[70:73]
	v_mfma_f32_16x16x32_bf16 v[66:69], v[164:167], v[208:211], v[66:69]
	v_mfma_f32_16x16x32_bf16 v[114:117], v[160:163], v[176:179], v[114:117]
	v_mfma_f32_16x16x32_bf16 v[110:113], v[168:171], v[176:179], v[110:113]
	v_mfma_f32_16x16x32_bf16 v[98:101], v[160:163], v[184:187], v[98:101]
	v_mfma_f32_16x16x32_bf16 v[94:97], v[168:171], v[184:187], v[94:97]
	v_mfma_f32_16x16x32_bf16 v[82:85], v[160:163], v[204:207], v[82:85]
	v_mfma_f32_16x16x32_bf16 v[78:81], v[168:171], v[204:207], v[78:81]
	v_mfma_f32_16x16x32_bf16 v[70:73], v[160:163], v[212:215], v[70:73]
	v_mfma_f32_16x16x32_bf16 v[66:69], v[168:171], v[212:215], v[66:69]
	s_barrier
	s_add_i32 s36, s36, s29
	s_mov_b32 m0, s36
	ds_read_b128 v[172:175], v159 offset:16384
	ds_read_b128 v[176:179], v159 offset:17408
	ds_read_b128 v[180:183], v159 offset:18432
	ds_read_b128 v[184:187], v159 offset:19456
	ds_read_b128 v[188:191], v159 offset:20480
	ds_read_b128 v[204:207], v159 offset:21504
	ds_read_b128 v[208:211], v159 offset:22528
	ds_read_b128 v[212:215], v159 offset:23552
	global_load_lds_dwordx4 v0, s[18:19]
	s_add_i32 m0, s36, 0x2000
	s_add_u32 s64, s18, 0x4000
	s_addc_u32 s65, s19, 0
	s_add_i32 s36, s37, s29
	global_load_lds_dwordx4 v142, s[18:19]
	s_mov_b32 m0, s36
	s_nop 0
	global_load_lds_dwordx4 v0, s[64:65]
	s_add_i32 m0, s36, 0x2000
	s_nop 0
	global_load_lds_dwordx4 v142, s[64:65]
	s_mov_b32 m0, s30
	s_nop 0
	global_load_lds_dwordx4 v0, s[20:21]
	s_mov_b32 m0, s31
	s_nop 0
	global_load_lds_dwordx4 v142, s[20:21]
	s_waitcnt vmcnt(8)
	s_waitcnt lgkmcnt(0)
	s_barrier
	s_waitcnt lgkmcnt(0)
	v_mfma_f32_16x16x32_bf16 v[62:65], v[130:133], v[172:175], v[62:65]
	v_mfma_f32_16x16x32_bf16 v[58:61], v[138:141], v[172:175], v[58:61]
	v_mfma_f32_16x16x32_bf16 v[54:57], v[130:133], v[180:183], v[54:57]
	v_mfma_f32_16x16x32_bf16 v[42:45], v[138:141], v[180:183], v[42:45]
	v_mfma_f32_16x16x32_bf16 v[38:41], v[130:133], v[188:191], v[38:41]
	v_mfma_f32_16x16x32_bf16 v[26:29], v[138:141], v[188:191], v[26:29]
	v_mfma_f32_16x16x32_bf16 v[22:25], v[130:133], v[208:211], v[22:25]
	v_mfma_f32_16x16x32_bf16 v[10:13], v[138:141], v[208:211], v[10:13]
	v_mfma_f32_16x16x32_bf16 v[62:65], v[134:137], v[176:179], v[62:65]
	v_mfma_f32_16x16x32_bf16 v[58:61], v[148:151], v[176:179], v[58:61]
	v_mfma_f32_16x16x32_bf16 v[54:57], v[134:137], v[184:187], v[54:57]
	v_mfma_f32_16x16x32_bf16 v[42:45], v[148:151], v[184:187], v[42:45]
	v_mfma_f32_16x16x32_bf16 v[38:41], v[134:137], v[204:207], v[38:41]
	v_mfma_f32_16x16x32_bf16 v[26:29], v[148:151], v[204:207], v[26:29]
	v_mfma_f32_16x16x32_bf16 v[22:25], v[134:137], v[212:215], v[22:25]
	v_mfma_f32_16x16x32_bf16 v[10:13], v[148:151], v[212:215], v[10:13]
	v_mfma_f32_16x16x32_bf16 v[50:53], v[152:155], v[172:175], v[50:53]
	v_mfma_f32_16x16x32_bf16 v[46:49], v[164:167], v[172:175], v[46:49]
	v_mfma_f32_16x16x32_bf16 v[34:37], v[152:155], v[180:183], v[34:37]
	v_mfma_f32_16x16x32_bf16 v[30:33], v[164:167], v[180:183], v[30:33]
	v_mfma_f32_16x16x32_bf16 v[18:21], v[152:155], v[188:191], v[18:21]
	v_mfma_f32_16x16x32_bf16 v[14:17], v[164:167], v[188:191], v[14:17]
	v_mfma_f32_16x16x32_bf16 v[6:9], v[152:155], v[208:211], v[6:9]
	v_mfma_f32_16x16x32_bf16 v[2:5], v[164:167], v[208:211], v[2:5]
	v_mfma_f32_16x16x32_bf16 v[50:53], v[160:163], v[176:179], v[50:53]
	v_mfma_f32_16x16x32_bf16 v[46:49], v[168:171], v[176:179], v[46:49]
	v_mfma_f32_16x16x32_bf16 v[34:37], v[160:163], v[184:187], v[34:37]
	v_mfma_f32_16x16x32_bf16 v[30:33], v[168:171], v[184:187], v[30:33]
	v_mfma_f32_16x16x32_bf16 v[18:21], v[160:163], v[204:207], v[18:21]
	v_mfma_f32_16x16x32_bf16 v[14:17], v[168:171], v[204:207], v[14:17]
	v_mfma_f32_16x16x32_bf16 v[6:9], v[160:163], v[212:215], v[6:9]
	v_mfma_f32_16x16x32_bf16 v[2:5], v[168:171], v[212:215], v[2:5]
	s_barrier
; #define PG8_STAGE(bufoff, gbase, voff) do { _Pragma("unroll") for (int _i = 0; _i < 2; ++_i) \
;         __builtin_amdgcn_global_load_lds((const unsigned*)((const char*)(gbase) + (voff)[_i]), (LAS unsigned*)(lds + (bufoff) + ldsw + _i * 8192), 16, 0, 0); } while (0)
; #define PG8_LDA(dst, b, h) do { _Pragma("unroll") for (int m = 0; m < 4; ++m) _Pragma("unroll") for (int k = 0; k < 2; ++k) dst[m][k] = *(const LAS bf16x8*)(lds + PG8_SA(b, h) + aoff + m * 2048 + k * 1024); } while (0)
; #define PG8_LDB(dst, b, h) do { _Pragma("unroll") for (int n = 0; n < 2; ++n) _Pragma("unroll") for (int k = 0; k < 2; ++k) dst[n][k] = *(const LAS bf16x8*)(lds + PG8_SB(b, h) + boff + n * 2048 + k * 1024); } while (0)
; #define PG8_MMA(ai, bj, At, Bt) do { __builtin_amdgcn_s_setprio(1); _Pragma("unroll") for (int m = 0; m < 4; ++m) _Pragma("unroll") for (int n = 0; n < 2; ++n) _Pragma("unroll") for (int k = 0; k < 2; ++k) \
;         acc[ai][bj][m][n] = __builtin_amdgcn_mfma_f32_16x16x32_bf16(Bt[n][k], At[m][k], acc[ai][bj][m][n], 0, 0, 0); __builtin_amdgcn_s_setprio(0); } while (0)
; #define PG8_WAIT_V(n) asm volatile("s_waitcnt vmcnt(" #n ")" ::: "memory")
; #define PG8_WAIT_L(n) asm volatile("s_waitcnt lgkmcnt(" #n ")" ::: "memory")
; #define PG8_BAR __builtin_amdgcn_s_barrier()
; #define PG8_SCHED __builtin_amdgcn_sched_barrier(0)
; template <class Epi, class Sched>
; __device__ __forceinline__ void gemm_phase(const int tid, LAS unsigned char* lds, const Gemm g, const Sched& S, const Epi& E) {
;     ...
;             PG8_LDB(B0, 1, 0); PG8_LDB(B1, 1, 1); PG8_SCHED; PG8_LDA(At, 1, 0); PG8_STAGE(PG8_SA(0, 1), a2 + hstepA, voffA);
;             PG8_WAIT_V(8); PG8_WAIT_L(0); PG8_BAR; PG8_MMA(0, 0, At, B0); PG8_MMA(0, 1, At, B1); PG8_BAR; PG8_SCHED;
;             PG8_LDA(At, 1, 1); PG8_STAGE(PG8_SB(1, 0), b3, voffB); PG8_STAGE(PG8_SB(1, 1), b3 + hstepB, voffB); PG8_STAGE(PG8_SA(1, 0), a3, voffA);
;             PG8_WAIT_V(8); PG8_WAIT_L(0); PG8_BAR; PG8_MMA(1, 0, At, B0); PG8_MMA(1, 1, At, B1); PG8_BAR; PG8_SCHED;
;         }
;         if (wr == 0) PG8_BAR;
	s_add_i32 s36, 16, 0x18000
	s_add_i32 s37, 16, 0x1c000
	v_add_u32_e32 v148, s36, v157
	v_add_u32_e32 v168, s37, v157
	ds_read_b128 v[130:133], v148
	ds_read_b128 v[134:137], v148 offset:1024
	ds_read_b128 v[138:141], v148 offset:2048
	ds_read_b128 v[148:151], v148 offset:3072
	ds_read_b128 v[152:155], v168
	ds_read_b128 v[160:163], v168 offset:1024
	ds_read_b128 v[164:167], v168 offset:2048
	ds_read_b128 v[168:171], v168 offset:3072
	s_add_u32 s20, s20, 0x4000
	s_addc_u32 s21, s21, 0
	s_mov_b32 m0, s34
	ds_read_b128 v[172:175], v159 offset:32768
	ds_read_b128 v[176:179], v159 offset:33792
	ds_read_b128 v[180:183], v159 offset:34816
	ds_read_b128 v[184:187], v159 offset:35840
	ds_read_b128 v[188:191], v159 offset:36864
	ds_read_b128 v[204:207], v159 offset:37888
	ds_read_b128 v[208:211], v159 offset:38912
	ds_read_b128 v[212:215], v159 offset:39936
	global_load_lds_dwordx4 v0, s[20:21]
	s_mov_b32 m0, s35
	s_nop 0
	global_load_lds_dwordx4 v142, s[20:21]
	s_waitcnt vmcnt(8)
	s_waitcnt lgkmcnt(0)
	s_barrier
	s_waitcnt lgkmcnt(0)
	v_mfma_f32_16x16x32_bf16 v[126:129], v[130:133], v[172:175], v[126:129]
	v_mfma_f32_16x16x32_bf16 v[122:125], v[138:141], v[172:175], v[122:125]
	v_mfma_f32_16x16x32_bf16 v[118:121], v[130:133], v[180:183], v[118:121]
	v_mfma_f32_16x16x32_bf16 v[106:109], v[138:141], v[180:183], v[106:109]
	v_mfma_f32_16x16x32_bf16 v[102:105], v[130:133], v[188:191], v[102:105]
	v_mfma_f32_16x16x32_bf16 v[90:93], v[138:141], v[188:191], v[90:93]
	v_mfma_f32_16x16x32_bf16 v[86:89], v[130:133], v[208:211], v[86:89]
	v_mfma_f32_16x16x32_bf16 v[74:77], v[138:141], v[208:211], v[74:77]
	v_mfma_f32_16x16x32_bf16 v[126:129], v[134:137], v[176:179], v[126:129]
	v_mfma_f32_16x16x32_bf16 v[122:125], v[148:151], v[176:179], v[122:125]
	v_mfma_f32_16x16x32_bf16 v[118:121], v[134:137], v[184:187], v[118:121]
	v_mfma_f32_16x16x32_bf16 v[106:109], v[148:151], v[184:187], v[106:109]
	v_mfma_f32_16x16x32_bf16 v[102:105], v[134:137], v[204:207], v[102:105]
	v_mfma_f32_16x16x32_bf16 v[90:93], v[148:151], v[204:207], v[90:93]
	v_mfma_f32_16x16x32_bf16 v[86:89], v[134:137], v[212:215], v[86:89]
	v_mfma_f32_16x16x32_bf16 v[74:77], v[148:151], v[212:215], v[74:77]
	v_mfma_f32_16x16x32_bf16 v[114:117], v[152:155], v[172:175], v[114:117]
	v_mfma_f32_16x16x32_bf16 v[110:113], v[164:167], v[172:175], v[110:113]
	v_mfma_f32_16x16x32_bf16 v[98:101], v[152:155], v[180:183], v[98:101]
	v_mfma_f32_16x16x32_bf16 v[94:97], v[164:167], v[180:183], v[94:97]
	v_mfma_f32_16x16x32_bf16 v[82:85], v[152:155], v[188:191], v[82:85]
	v_mfma_f32_16x16x32_bf16 v[78:81], v[164:167], v[188:191], v[78:81]
	v_mfma_f32_16x16x32_bf16 v[70:73], v[152:155], v[208:211], v[70:73]
	v_mfma_f32_16x16x32_bf16 v[66:69], v[164:167], v[208:211], v[66:69]
	v_mfma_f32_16x16x32_bf16 v[114:117], v[160:163], v[176:179], v[114:117]
	v_mfma_f32_16x16x32_bf16 v[110:113], v[168:171], v[176:179], v[110:113]
	v_mfma_f32_16x16x32_bf16 v[98:101], v[160:163], v[184:187], v[98:101]
	v_mfma_f32_16x16x32_bf16 v[94:97], v[168:171], v[184:187], v[94:97]
	v_mfma_f32_16x16x32_bf16 v[82:85], v[160:163], v[204:207], v[82:85]
	v_mfma_f32_16x16x32_bf16 v[78:81], v[168:171], v[204:207], v[78:81]
	v_mfma_f32_16x16x32_bf16 v[70:73], v[160:163], v[212:215], v[70:73]
	v_mfma_f32_16x16x32_bf16 v[66:69], v[168:171], v[212:215], v[66:69]
	s_barrier
	s_add_u32 s20, s18, 0x8000
	s_addc_u32 s21, s19, 0
	s_add_i32 s36, s36, s29
	s_mov_b32 m0, s36
	ds_read_b128 v[172:175], v159 offset:49152
	ds_read_b128 v[176:179], v159 offset:50176
	ds_read_b128 v[180:183], v159 offset:51200
	ds_read_b128 v[184:187], v159 offset:52224
	ds_read_b128 v[188:191], v159 offset:53248
	ds_read_b128 v[204:207], v159 offset:54272
	ds_read_b128 v[208:211], v159 offset:55296
	ds_read_b128 v[212:215], v159 offset:56320
	global_load_lds_dwordx4 v0, s[20:21]
	s_add_i32 m0, s36, 0x2000
	s_add_u32 s18, s18, 0xc000
	s_addc_u32 s19, s19, 0
	global_load_lds_dwordx4 v142, s[20:21]
	s_add_i32 s20, s37, s29
	s_mov_b32 m0, s20
	s_nop 0
	global_load_lds_dwordx4 v0, s[18:19]
	s_add_i32 m0, s20, 0x2000
	s_nop 0
	global_load_lds_dwordx4 v142, s[18:19]
	s_mov_b32 m0, s53
	s_nop 0
	global_load_lds_dwordx4 v0, s[16:17]
	s_mov_b32 m0, s54
	s_nop 0
	global_load_lds_dwordx4 v142, s[16:17]
	s_waitcnt vmcnt(8)
	s_waitcnt lgkmcnt(0)
	s_barrier
	s_waitcnt lgkmcnt(0)
	v_mfma_f32_16x16x32_bf16 v[62:65], v[130:133], v[172:175], v[62:65]
	v_mfma_f32_16x16x32_bf16 v[58:61], v[138:141], v[172:175], v[58:61]
	v_mfma_f32_16x16x32_bf16 v[54:57], v[130:133], v[180:183], v[54:57]
	v_mfma_f32_16x16x32_bf16 v[42:45], v[138:141], v[180:183], v[42:45]
	v_mfma_f32_16x16x32_bf16 v[38:41], v[130:133], v[188:191], v[38:41]
	v_mfma_f32_16x16x32_bf16 v[26:29], v[138:141], v[188:191], v[26:29]
	v_mfma_f32_16x16x32_bf16 v[22:25], v[130:133], v[208:211], v[22:25]
	v_mfma_f32_16x16x32_bf16 v[10:13], v[138:141], v[208:211], v[10:13]
	v_mfma_f32_16x16x32_bf16 v[62:65], v[134:137], v[176:179], v[62:65]
	v_mfma_f32_16x16x32_bf16 v[58:61], v[148:151], v[176:179], v[58:61]
	v_mfma_f32_16x16x32_bf16 v[54:57], v[134:137], v[184:187], v[54:57]
	v_mfma_f32_16x16x32_bf16 v[42:45], v[148:151], v[184:187], v[42:45]
	v_mfma_f32_16x16x32_bf16 v[38:41], v[134:137], v[204:207], v[38:41]
	v_mfma_f32_16x16x32_bf16 v[26:29], v[148:151], v[204:207], v[26:29]
	v_mfma_f32_16x16x32_bf16 v[22:25], v[134:137], v[212:215], v[22:25]
	v_mfma_f32_16x16x32_bf16 v[10:13], v[148:151], v[212:215], v[10:13]
	v_mfma_f32_16x16x32_bf16 v[50:53], v[152:155], v[172:175], v[50:53]
	v_mfma_f32_16x16x32_bf16 v[46:49], v[164:167], v[172:175], v[46:49]
	v_mfma_f32_16x16x32_bf16 v[34:37], v[152:155], v[180:183], v[34:37]
	v_mfma_f32_16x16x32_bf16 v[30:33], v[164:167], v[180:183], v[30:33]
	v_mfma_f32_16x16x32_bf16 v[18:21], v[152:155], v[188:191], v[18:21]
	v_mfma_f32_16x16x32_bf16 v[14:17], v[164:167], v[188:191], v[14:17]
	v_mfma_f32_16x16x32_bf16 v[6:9], v[152:155], v[208:211], v[6:9]
	v_mfma_f32_16x16x32_bf16 v[2:5], v[164:167], v[208:211], v[2:5]
	v_mfma_f32_16x16x32_bf16 v[50:53], v[160:163], v[176:179], v[50:53]
	v_mfma_f32_16x16x32_bf16 v[46:49], v[168:171], v[176:179], v[46:49]
	v_mfma_f32_16x16x32_bf16 v[34:37], v[160:163], v[184:187], v[34:37]
	v_mfma_f32_16x16x32_bf16 v[30:33], v[168:171], v[184:187], v[30:33]
	v_mfma_f32_16x16x32_bf16 v[18:21], v[160:163], v[204:207], v[18:21]
	v_mfma_f32_16x16x32_bf16 v[14:17], v[168:171], v[204:207], v[14:17]
	v_mfma_f32_16x16x32_bf16 v[6:9], v[160:163], v[212:215], v[6:9]
	v_mfma_f32_16x16x32_bf16 v[2:5], v[168:171], v[212:215], v[2:5]
	s_barrier
	s_add_i32 s62, s62, 2
	s_add_u32 s60, s60, 0x10000
	s_addc_u32 s61, s61, 0
	s_add_u32 s14, s14, 0x10000
	s_addc_u32 s15, s15, 0
	s_cmpk_gt_u32 s62, 0x55
	s_cbranch_scc0 .LBB0_1171
	s_and_b64 vcc, exec, s[10:11]
	s_cbranch_vccz .LBB0_1174
	s_barrier
